# v24 + nt (streaming) hint on the prologue's one-shot f32 input loads
# speedup vs baseline: 1.0052x; 1.0052x over previous
.LBB0_22:
	s_lshl_b32 s56, s16, 1
	s_lshl_b32 s57, s9, 1
	v_add_u32_e32 v48, s56, v2
	v_add_u32_e32 v50, s57, v19
	v_add_u32_e32 v52, s56, v26
	v_add_u32_e32 v54, s57, v21
	v_add_u32_e32 v56, s56, v28
	v_add_u32_e32 v58, s57, v23
	v_add_u32_e32 v60, s56, v30
	v_add_u32_e32 v62, s57, v27
	v_add_u32_e32 v64, s56, v32
	v_add_u32_e32 v66, s57, v29
	v_add_u32_e32 v68, s56, v34
	v_add_u32_e32 v70, s57, v31
	v_add_u32_e32 v72, s56, v36
	v_add_u32_e32 v74, s57, v33
	v_add_u32_e32 v76, s56, v38
	v_add_u32_e32 v78, s57, v35
	v_ashrrev_i32_e32 v49, 31, v48
	v_ashrrev_i32_e32 v51, 31, v50
	v_ashrrev_i32_e32 v53, 31, v52
	v_ashrrev_i32_e32 v55, 31, v54
	v_ashrrev_i32_e32 v57, 31, v56
	v_ashrrev_i32_e32 v59, 31, v58
	v_ashrrev_i32_e32 v61, 31, v60
	v_ashrrev_i32_e32 v63, 31, v62
	v_ashrrev_i32_e32 v65, 31, v64
	v_ashrrev_i32_e32 v67, 31, v66
	v_ashrrev_i32_e32 v69, 31, v68
	v_ashrrev_i32_e32 v71, 31, v70
	v_ashrrev_i32_e32 v73, 31, v72
	v_ashrrev_i32_e32 v75, 31, v74
	v_ashrrev_i32_e32 v77, 31, v76
	v_ashrrev_i32_e32 v79, 31, v78
	v_lshlrev_b64 v[48:49], 12, v[48:49]
	v_lshlrev_b64 v[50:51], 12, v[50:51]
	v_lshlrev_b64 v[52:53], 12, v[52:53]
	v_lshlrev_b64 v[54:55], 12, v[54:55]
	v_lshlrev_b64 v[56:57], 12, v[56:57]
	v_lshlrev_b64 v[58:59], 12, v[58:59]
	v_lshlrev_b64 v[60:61], 12, v[60:61]
	v_lshlrev_b64 v[62:63], 12, v[62:63]
	v_lshlrev_b64 v[64:65], 12, v[64:65]
	v_lshlrev_b64 v[66:67], 12, v[66:67]
	v_lshlrev_b64 v[68:69], 12, v[68:69]
	v_lshlrev_b64 v[70:71], 12, v[70:71]
	v_lshlrev_b64 v[72:73], 12, v[72:73]
	v_lshlrev_b64 v[74:75], 12, v[74:75]
	v_lshlrev_b64 v[76:77], 12, v[76:77]
	v_lshlrev_b64 v[78:79], 12, v[78:79]
	v_lshl_add_u64 v[48:49], v[24:25], 0, v[48:49]
	v_lshl_add_u64 v[50:51], v[24:25], 0, v[50:51]
	v_lshl_add_u64 v[52:53], v[24:25], 0, v[52:53]
	v_lshl_add_u64 v[54:55], v[24:25], 0, v[54:55]
	v_lshl_add_u64 v[56:57], v[24:25], 0, v[56:57]
	v_lshl_add_u64 v[58:59], v[24:25], 0, v[58:59]
	v_lshl_add_u64 v[60:61], v[24:25], 0, v[60:61]
	v_lshl_add_u64 v[62:63], v[24:25], 0, v[62:63]
	v_lshl_add_u64 v[64:65], v[24:25], 0, v[64:65]
	v_lshl_add_u64 v[66:67], v[24:25], 0, v[66:67]
	v_lshl_add_u64 v[68:69], v[24:25], 0, v[68:69]
	v_lshl_add_u64 v[70:71], v[24:25], 0, v[70:71]
	v_lshl_add_u64 v[72:73], v[24:25], 0, v[72:73]
	v_lshl_add_u64 v[74:75], v[24:25], 0, v[74:75]
	v_lshl_add_u64 v[76:77], v[24:25], 0, v[76:77]
	v_lshl_add_u64 v[78:79], v[24:25], 0, v[78:79]
	global_load_dword v37, v[48:49], off nt
	global_load_dword v40, v[50:51], off nt
	global_load_dword v47, v[52:53], off nt
	global_load_dword v80, v[54:55], off nt
	global_load_dword v81, v[56:57], off nt
	global_load_dword v82, v[58:59], off nt
	global_load_dword v83, v[60:61], off nt
	global_load_dword v84, v[62:63], off nt
	global_load_dword v85, v[64:65], off nt
	global_load_dword v86, v[66:67], off nt
	global_load_dword v87, v[68:69], off nt
	global_load_dword v88, v[70:71], off nt
	global_load_dword v89, v[72:73], off nt
	global_load_dword v90, v[74:75], off nt
	global_load_dword v91, v[76:77], off nt
	global_load_dword v92, v[78:79], off nt
	s_add_i32 s16, s16, 16
	s_add_i32 s9, s9, 16
	s_add_i32 s17, s17, -16
	v_add_u32_e32 v48, s56, v0
	v_add_u32_e32 v50, s57, v1
	v_add_u32_e32 v52, s56, v8
	v_add_u32_e32 v54, s57, v5
	v_add_u32_e32 v56, s56, v10
	v_add_u32_e32 v58, s57, v7
	v_add_u32_e32 v60, s56, v12
	v_add_u32_e32 v62, s57, v9
	v_add_u32_e32 v64, s56, v14
	v_add_u32_e32 v66, s57, v11
	v_add_u32_e32 v68, s56, v16
	v_add_u32_e32 v70, s57, v13
	v_add_u32_e32 v72, s56, v18
	v_add_u32_e32 v74, s57, v15
	v_add_u32_e32 v76, s56, v20
	v_add_u32_e32 v78, s57, v17
	s_cmp_lg_u32 s17, 0
	v_mad_u64_u32 v[48:49], s[56:57], v48, s35, v[4:5]
	v_mad_u64_u32 v[50:51], s[56:57], v50, s35, v[4:5]
	v_mad_u64_u32 v[52:53], s[56:57], v52, s35, v[4:5]
	v_mad_u64_u32 v[54:55], s[56:57], v54, s35, v[4:5]
	v_mad_u64_u32 v[56:57], s[56:57], v56, s35, v[4:5]
	v_mad_u64_u32 v[58:59], s[56:57], v58, s35, v[4:5]
	v_mad_u64_u32 v[60:61], s[56:57], v60, s35, v[4:5]
	v_mad_u64_u32 v[62:63], s[56:57], v62, s35, v[4:5]
	v_mad_u64_u32 v[64:65], s[56:57], v64, s35, v[4:5]
	v_mad_u64_u32 v[66:67], s[56:57], v66, s35, v[4:5]
	v_mad_u64_u32 v[68:69], s[56:57], v68, s35, v[4:5]
	v_mad_u64_u32 v[70:71], s[56:57], v70, s35, v[4:5]
	v_mad_u64_u32 v[72:73], s[56:57], v72, s35, v[4:5]
	v_mad_u64_u32 v[74:75], s[56:57], v74, s35, v[4:5]
	v_mad_u64_u32 v[76:77], s[56:57], v76, s35, v[4:5]
	v_mad_u64_u32 v[78:79], s[56:57], v78, s35, v[4:5]
	s_waitcnt vmcnt(15)
	ds_write_b32 v48, v37
	s_waitcnt vmcnt(14)
	ds_write_b32 v50, v40
	s_waitcnt vmcnt(13)
	ds_write_b32 v52, v47
	s_waitcnt vmcnt(12)
	ds_write_b32 v54, v80
	s_waitcnt vmcnt(11)
	ds_write_b32 v56, v81
	s_waitcnt vmcnt(10)
	ds_write_b32 v58, v82
	s_waitcnt vmcnt(9)
	ds_write_b32 v60, v83
	s_waitcnt vmcnt(8)
	ds_write_b32 v62, v84
	s_waitcnt vmcnt(7)
	ds_write_b32 v64, v85
	s_waitcnt vmcnt(6)
	ds_write_b32 v66, v86
	s_waitcnt vmcnt(5)
	ds_write_b32 v68, v87
	s_waitcnt vmcnt(4)
	ds_write_b32 v70, v88
	s_waitcnt vmcnt(3)
	ds_write_b32 v72, v89
	s_waitcnt vmcnt(2)
	ds_write_b32 v74, v90
	s_waitcnt vmcnt(1)
	ds_write_b32 v76, v91
	s_waitcnt vmcnt(0)
	ds_write_b32 v78, v92
	s_cbranch_scc1 .LBB0_22
	s_waitcnt lgkmcnt(0)
	s_lshl_b64 s[16:17], s[6:7], 19
	ds_read2_b32 v[28:29], v42 offset1:8
	s_add_u32 s7, s19, s16
	ds_read2_b32 v[32:33], v42 offset0:33 offset1:41
	s_addc_u32 s9, s20, s17
	s_lshl_b32 s8, s8, 1
	s_add_u32 s8, s7, s8
	ds_read2_b32 v[34:35], v42 offset0:66 offset1:74
	s_addc_u32 s9, s9, 0
	v_lshlrev_b32_e32 v2, 1, v6
	ds_read2_b32 v[36:37], v42 offset0:99 offset1:107
	v_lshl_add_u64 v[30:31], s[8:9], 0, v[2:3]
	s_waitcnt lgkmcnt(3)
	v_bfe_u32 v2, v28, 16, 1
	v_add3_u32 v2, v28, v2, s37
	s_waitcnt lgkmcnt(2)
	v_bfe_u32 v19, v32, 16, 1
	ds_read2_b32 v[48:49], v42 offset0:132 offset1:140
	v_lshrrev_b32_e32 v2, 16, v2
	v_add3_u32 v19, v32, v19, s37
	ds_read2_b32 v[50:51], v42 offset0:165 offset1:173
	v_and_or_b32 v24, v19, s38, v2
	s_waitcnt lgkmcnt(3)
	v_bfe_u32 v2, v34, 16, 1
	v_add3_u32 v2, v34, v2, s37
	s_waitcnt lgkmcnt(2)
	v_bfe_u32 v19, v36, 16, 1
	ds_read2_b32 v[52:53], v42 offset0:198 offset1:206
	v_lshrrev_b32_e32 v2, 16, v2
	v_add3_u32 v19, v36, v19, s37
	ds_read2_b32 v[54:55], v42 offset0:231 offset1:239
	v_and_or_b32 v25, v19, s38, v2
	s_waitcnt lgkmcnt(3)
	v_bfe_u32 v2, v48, 16, 1
	v_add3_u32 v2, v48, v2, s37
	s_waitcnt lgkmcnt(2)
	v_bfe_u32 v19, v50, 16, 1
	v_lshrrev_b32_e32 v2, 16, v2
	v_add3_u32 v19, v50, v19, s37
	v_and_or_b32 v26, v19, s38, v2
	s_waitcnt lgkmcnt(1)
	v_bfe_u32 v2, v52, 16, 1
	v_add3_u32 v2, v52, v2, s37
	s_waitcnt lgkmcnt(0)
	v_bfe_u32 v19, v54, 16, 1
	v_lshrrev_b32_e32 v2, 16, v2
	v_add3_u32 v19, v54, v19, s37
	v_add_u32_e32 v56, s2, v41
	v_and_or_b32 v27, v19, s38, v2
	v_ashrrev_i32_e32 v57, 31, v56
	v_bfe_u32 v2, v29, 16, 1
	v_lshlrev_b64 v[56:57], 9, v[56:57]
	v_add3_u32 v2, v29, v2, s37
	v_bfe_u32 v19, v33, 16, 1
	v_lshl_add_u64 v[56:57], v[30:31], 0, v[56:57]
	v_lshrrev_b32_e32 v2, 16, v2
	v_add3_u32 v19, v33, v19, s37
	global_store_dwordx4 v[56:57], v[24:27], off
	v_add_u32_e32 v28, s2, v43
	v_ashrrev_i32_e32 v29, 31, v28
	v_and_or_b32 v24, v19, s38, v2
	v_bfe_u32 v2, v35, 16, 1
	v_add3_u32 v2, v35, v2, s37
	v_bfe_u32 v19, v37, 16, 1
	v_lshrrev_b32_e32 v2, 16, v2
	v_add3_u32 v19, v37, v19, s37
	v_and_or_b32 v25, v19, s38, v2
	v_bfe_u32 v2, v49, 16, 1
	v_add3_u32 v2, v49, v2, s37
	v_bfe_u32 v19, v51, 16, 1
	v_lshrrev_b32_e32 v2, 16, v2
	v_add3_u32 v19, v51, v19, s37
	v_and_or_b32 v26, v19, s38, v2
	v_bfe_u32 v2, v53, 16, 1
	v_add3_u32 v2, v53, v2, s37
	v_bfe_u32 v19, v55, 16, 1
	v_lshrrev_b32_e32 v2, 16, v2
	v_add3_u32 v19, v55, v19, s37
	v_lshlrev_b64 v[28:29], 9, v[28:29]
	v_and_or_b32 v27, v19, s38, v2
	ds_read2_b32 v[32:33], v42 offset0:16 offset1:24
	v_lshl_add_u64 v[28:29], v[30:31], 0, v[28:29]
	global_store_dwordx4 v[28:29], v[24:27], off
	ds_read2_b32 v[28:29], v42 offset0:49 offset1:57
	ds_read2_b32 v[34:35], v42 offset0:82 offset1:90
	ds_read2_b32 v[36:37], v42 offset0:115 offset1:123
	s_waitcnt lgkmcnt(3)
	v_bfe_u32 v2, v32, 16, 1
	v_add3_u32 v2, v32, v2, s37
	s_waitcnt lgkmcnt(2)
	v_bfe_u32 v19, v28, 16, 1
	ds_read2_b32 v[48:49], v42 offset0:148 offset1:156
	v_lshrrev_b32_e32 v2, 16, v2
	v_add3_u32 v19, v28, v19, s37
	ds_read2_b32 v[50:51], v42 offset0:181 offset1:189
	v_and_or_b32 v24, v19, s38, v2
	s_waitcnt lgkmcnt(3)
	v_bfe_u32 v2, v34, 16, 1
	v_add3_u32 v2, v34, v2, s37
	s_waitcnt lgkmcnt(2)
	v_bfe_u32 v19, v36, 16, 1
	ds_read2_b32 v[52:53], v42 offset0:214 offset1:222
	v_lshrrev_b32_e32 v2, 16, v2
	v_add3_u32 v19, v36, v19, s37
	ds_read2_b32 v[54:55], v42 offset0:247 offset1:255
	v_and_or_b32 v25, v19, s38, v2
	s_waitcnt lgkmcnt(3)
	v_bfe_u32 v2, v48, 16, 1
	v_add3_u32 v2, v48, v2, s37
	s_waitcnt lgkmcnt(2)
	v_bfe_u32 v19, v50, 16, 1
	v_lshrrev_b32_e32 v2, 16, v2
	v_add3_u32 v19, v50, v19, s37
	v_and_or_b32 v26, v19, s38, v2
	s_waitcnt lgkmcnt(1)
	v_bfe_u32 v2, v52, 16, 1
	v_add3_u32 v2, v52, v2, s37
	s_waitcnt lgkmcnt(0)
	v_bfe_u32 v19, v54, 16, 1
	v_lshrrev_b32_e32 v2, 16, v2
	v_add3_u32 v19, v54, v19, s37
	v_add_u32_e32 v56, s2, v44
	v_and_or_b32 v27, v19, s38, v2
	v_ashrrev_i32_e32 v57, 31, v56
	v_bfe_u32 v19, v33, 16, 1
	v_lshlrev_b64 v[56:57], 9, v[56:57]
	v_bfe_u32 v2, v29, 16, 1
	v_add3_u32 v19, v33, v19, s37
	v_lshl_add_u64 v[56:57], v[30:31], 0, v[56:57]
	v_add3_u32 v2, v29, v2, s37
	v_lshrrev_b32_e32 v19, 16, v19
	global_store_dwordx4 v[56:57], v[24:27], off
	v_add_u32_e32 v28, s2, v45
	v_ashrrev_i32_e32 v29, 31, v28
	v_and_or_b32 v24, v2, s38, v19
	v_bfe_u32 v19, v35, 16, 1
	v_bfe_u32 v2, v37, 16, 1
	v_add3_u32 v19, v35, v19, s37
	v_add3_u32 v2, v37, v2, s37
	v_lshrrev_b32_e32 v19, 16, v19
	v_and_or_b32 v25, v2, s38, v19
	v_bfe_u32 v19, v49, 16, 1
	v_bfe_u32 v2, v51, 16, 1
	v_add3_u32 v19, v49, v19, s37
	v_add3_u32 v2, v51, v2, s37
	v_lshrrev_b32_e32 v19, 16, v19
	v_and_or_b32 v26, v2, s38, v19
	v_bfe_u32 v19, v53, 16, 1
	v_bfe_u32 v2, v55, 16, 1
	v_add3_u32 v19, v53, v19, s37
	v_add3_u32 v2, v55, v2, s37
	v_lshrrev_b32_e32 v19, 16, v19
	v_lshlrev_b64 v[28:29], 9, v[28:29]
	v_and_or_b32 v27, v2, s38, v19
	v_lshl_add_u64 v[28:29], v[30:31], 0, v[28:29]
	global_store_dwordx4 v[28:29], v[24:27], off
	s_waitcnt lgkmcnt(0)
	s_mov_b64 s[8:9], 0

.LBB0_26:
	s_lshl_b32 s17, s9, 1
	s_lshl_b32 s58, s8, 1
	v_add_u32_e32 v37, s17, v2
	v_add_u32_e32 v40, s58, v19
	v_add_u32_e32 v47, s17, v26
	v_add_u32_e32 v54, s58, v21
	v_add_u32_e32 v56, s17, v28
	v_add_u32_e32 v58, s58, v23
	v_add_u32_e32 v60, s17, v30
	v_add_u32_e32 v62, s58, v27
	v_add_u32_e32 v64, s17, v32
	v_add_u32_e32 v66, s58, v29
	v_add_u32_e32 v68, s17, v34
	v_add_u32_e32 v70, s58, v31
	v_add_u32_e32 v72, s17, v36
	v_add_u32_e32 v74, s58, v33
	v_add_u32_e32 v76, s17, v38
	v_add_u32_e32 v78, s58, v35
	v_mad_i64_i32 v[48:49], s[56:57], v37, s40, v[24:25]
	v_mad_i64_i32 v[50:51], s[56:57], v40, s40, v[24:25]
	v_mad_i64_i32 v[52:53], s[56:57], v47, s40, v[24:25]
	v_mad_i64_i32 v[54:55], s[56:57], v54, s40, v[24:25]
	v_mad_i64_i32 v[56:57], s[56:57], v56, s40, v[24:25]
	v_mad_i64_i32 v[58:59], s[56:57], v58, s40, v[24:25]
	v_mad_i64_i32 v[60:61], s[56:57], v60, s40, v[24:25]
	v_mad_i64_i32 v[62:63], s[56:57], v62, s40, v[24:25]
	v_mad_i64_i32 v[64:65], s[56:57], v64, s40, v[24:25]
	v_mad_i64_i32 v[66:67], s[56:57], v66, s40, v[24:25]
	v_mad_i64_i32 v[68:69], s[56:57], v68, s40, v[24:25]
	v_mad_i64_i32 v[70:71], s[56:57], v70, s40, v[24:25]
	v_mad_i64_i32 v[72:73], s[56:57], v72, s40, v[24:25]
	v_mad_i64_i32 v[74:75], s[56:57], v74, s40, v[24:25]
	v_mad_i64_i32 v[76:77], s[56:57], v76, s40, v[24:25]
	v_mad_i64_i32 v[78:79], s[56:57], v78, s40, v[24:25]
	global_load_dword v37, v[48:49], off nt
	global_load_dword v40, v[50:51], off nt
	global_load_dword v47, v[52:53], off nt
	global_load_dword v80, v[54:55], off nt
	global_load_dword v81, v[56:57], off nt
	global_load_dword v82, v[58:59], off nt
	global_load_dword v83, v[60:61], off nt
	global_load_dword v84, v[62:63], off nt
	global_load_dword v85, v[64:65], off nt
	global_load_dword v86, v[66:67], off nt
	global_load_dword v87, v[68:69], off nt
	global_load_dword v88, v[70:71], off nt
	global_load_dword v89, v[72:73], off nt
	global_load_dword v90, v[74:75], off nt
	global_load_dword v91, v[76:77], off nt
	global_load_dword v92, v[78:79], off nt
	s_add_i32 s9, s9, 16
	s_add_i32 s8, s8, 16
	s_add_i32 s16, s16, -16
	v_add_u32_e32 v48, s17, v0
	v_add_u32_e32 v50, s58, v1
	v_add_u32_e32 v52, s17, v8
	v_add_u32_e32 v54, s58, v5
	v_add_u32_e32 v56, s17, v10
	v_add_u32_e32 v58, s58, v7
	v_add_u32_e32 v60, s17, v12
	v_add_u32_e32 v62, s58, v9
	v_add_u32_e32 v64, s17, v14
	v_add_u32_e32 v66, s58, v11
	v_add_u32_e32 v68, s17, v16
	v_add_u32_e32 v70, s58, v13
	v_add_u32_e32 v72, s17, v18
	v_add_u32_e32 v74, s58, v15
	v_add_u32_e32 v76, s17, v20
	v_add_u32_e32 v78, s58, v17
	s_cmp_lg_u32 s16, 0
	v_mad_u64_u32 v[48:49], s[56:57], v48, s35, v[4:5]
	v_mad_u64_u32 v[50:51], s[56:57], v50, s35, v[4:5]
	v_mad_u64_u32 v[52:53], s[56:57], v52, s35, v[4:5]
	v_mad_u64_u32 v[54:55], s[56:57], v54, s35, v[4:5]
	v_mad_u64_u32 v[56:57], s[56:57], v56, s35, v[4:5]
	v_mad_u64_u32 v[58:59], s[56:57], v58, s35, v[4:5]
	v_mad_u64_u32 v[60:61], s[56:57], v60, s35, v[4:5]
	v_mad_u64_u32 v[62:63], s[56:57], v62, s35, v[4:5]
	v_mad_u64_u32 v[64:65], s[56:57], v64, s35, v[4:5]
	v_mad_u64_u32 v[66:67], s[56:57], v66, s35, v[4:5]
	v_mad_u64_u32 v[68:69], s[56:57], v68, s35, v[4:5]
	v_mad_u64_u32 v[70:71], s[56:57], v70, s35, v[4:5]
	v_mad_u64_u32 v[72:73], s[56:57], v72, s35, v[4:5]
	v_mad_u64_u32 v[74:75], s[56:57], v74, s35, v[4:5]
	v_mad_u64_u32 v[76:77], s[56:57], v76, s35, v[4:5]
	v_mad_u64_u32 v[78:79], s[56:57], v78, s35, v[4:5]
	s_waitcnt vmcnt(15)
	ds_write_b32 v48, v37
	s_waitcnt vmcnt(14)
	ds_write_b32 v50, v40
	s_waitcnt vmcnt(13)
	ds_write_b32 v52, v47
	s_waitcnt vmcnt(12)
	ds_write_b32 v54, v80
	s_waitcnt vmcnt(11)
	ds_write_b32 v56, v81
	s_waitcnt vmcnt(10)
	ds_write_b32 v58, v82
	s_waitcnt vmcnt(9)
	ds_write_b32 v60, v83
	s_waitcnt vmcnt(8)
	ds_write_b32 v62, v84
	s_waitcnt vmcnt(7)
	ds_write_b32 v64, v85
	s_waitcnt vmcnt(6)
	ds_write_b32 v66, v86
	s_waitcnt vmcnt(5)
	ds_write_b32 v68, v87
	s_waitcnt vmcnt(4)
	ds_write_b32 v70, v88
	s_waitcnt vmcnt(3)
	ds_write_b32 v72, v89
	s_waitcnt vmcnt(2)
	ds_write_b32 v74, v90
	s_waitcnt vmcnt(1)
	ds_write_b32 v76, v91
	s_waitcnt vmcnt(0)
	ds_write_b32 v78, v92
	s_cbranch_scc1 .LBB0_26
	s_waitcnt lgkmcnt(0)
	ds_read2_b32 v[34:35], v42 offset1:33
	ds_read2_b32 v[30:31], v42 offset0:66 offset1:99
	ds_read2_b32 v[28:29], v42 offset0:132 offset1:165
	ds_read2_b32 v[26:27], v42 offset0:198 offset1:231
	v_add_u32_e32 v2, s2, v41
	v_mul_hi_i32 v19, v2, s41
	v_lshrrev_b32_e32 v21, 31, v19
	v_ashrrev_i32_e32 v19, 5, v19
	v_add_u32_e32 v19, v19, v21
	v_mul_lo_u32 v21, v19, s42
	v_sub_u32_e32 v2, v2, v21
	v_cmp_lt_i32_e32 vcc, s43, v2
	s_and_saveexec_b64 s[8:9], vcc
	s_xor_b64 s[8:9], exec, s[8:9]
	v_and_b32_e32 v21, 0x7fffffe0, v2
	v_lshl_add_u32 v19, v19, 6, v21
	v_and_or_b32 v19, v2, 3, v19
	v_lshlrev_b32_e32 v21, 1, v2
	v_lshrrev_b32_e32 v2, 2, v2
	v_and_b32_e32 v21, 24, v21
	v_and_b32_e32 v2, 4, v2
	v_or3_b32 v2, v19, v21, v2
	v_add_u32_e32 v32, 0x180, v2
	s_andn2_saveexec_b64 s[8:9], s[8:9]
	v_lshl_add_u32 v32, v19, 7, v2
	s_or_b64 exec, exec, s[8:9]
	s_mul_i32 s9, s6, 0xc0000
	s_mul_hi_i32 s8, s6, 0xc0000
	s_add_u32 s9, s21, s9
	s_addc_u32 s16, s22, s8
	s_lshl_b32 s7, s7, 1
	s_add_u32 s8, s9, s7
	s_addc_u32 s9, s16, 0
	v_lshlrev_b32_e32 v2, 1, v6
	v_lshl_add_u64 v[24:25], s[8:9], 0, v[2:3]
	s_waitcnt lgkmcnt(3)
	v_bfe_u32 v2, v34, 16, 1
	v_add3_u32 v2, v34, v2, s37
	v_bfe_u32 v19, v35, 16, 1
	v_lshrrev_b32_e32 v2, 16, v2
	v_add3_u32 v19, v35, v19, s37
	v_and_or_b32 v34, v19, s38, v2
	s_waitcnt lgkmcnt(2)
	v_bfe_u32 v2, v30, 16, 1
	v_add3_u32 v2, v30, v2, s37
	v_bfe_u32 v19, v31, 16, 1
	v_lshrrev_b32_e32 v2, 16, v2
	v_add3_u32 v19, v31, v19, s37
	v_and_or_b32 v35, v19, s38, v2
	s_waitcnt lgkmcnt(1)
	v_bfe_u32 v2, v28, 16, 1
	v_add3_u32 v2, v28, v2, s37
	v_bfe_u32 v19, v29, 16, 1
	v_lshrrev_b32_e32 v2, 16, v2
	v_add3_u32 v19, v29, v19, s37
	v_and_or_b32 v36, v19, s38, v2
	s_waitcnt lgkmcnt(0)
	v_bfe_u32 v2, v26, 16, 1
	v_add3_u32 v2, v26, v2, s37
	v_bfe_u32 v19, v27, 16, 1
	v_ashrrev_i32_e32 v33, 31, v32
	v_lshrrev_b32_e32 v2, 16, v2
	v_add3_u32 v19, v27, v19, s37
	v_lshlrev_b64 v[26:27], 10, v[32:33]
	v_and_or_b32 v37, v19, s38, v2
	v_lshl_add_u64 v[26:27], v[24:25], 0, v[26:27]
	global_store_dwordx4 v[26:27], v[34:37], off
	ds_read2_b32 v[34:35], v42 offset0:8 offset1:41
	ds_read2_b32 v[30:31], v42 offset0:74 offset1:107
	ds_read2_b32 v[28:29], v42 offset0:140 offset1:173
	ds_read2_b32 v[26:27], v42 offset0:206 offset1:239
	v_add_u32_e32 v2, s2, v43
	v_mul_hi_i32 v19, v2, s41
	v_lshrrev_b32_e32 v21, 31, v19
	v_ashrrev_i32_e32 v19, 5, v19
	v_add_u32_e32 v19, v19, v21
	v_mul_lo_u32 v21, v19, s42
	v_sub_u32_e32 v2, v2, v21
	v_cmp_lt_i32_e32 vcc, s43, v2
	s_and_saveexec_b64 s[8:9], vcc
	s_xor_b64 s[8:9], exec, s[8:9]
	v_and_b32_e32 v21, 0x7fffffe0, v2
	v_lshl_add_u32 v19, v19, 6, v21
	v_and_or_b32 v19, v2, 3, v19
	v_lshlrev_b32_e32 v21, 1, v2
	v_lshrrev_b32_e32 v2, 2, v2
	v_and_b32_e32 v21, 24, v21
	v_and_b32_e32 v2, 4, v2
	v_or3_b32 v2, v19, v21, v2
	v_add_u32_e32 v32, 0x180, v2
	s_andn2_saveexec_b64 s[8:9], s[8:9]
	v_lshl_add_u32 v32, v19, 7, v2
	s_or_b64 exec, exec, s[8:9]
	s_waitcnt lgkmcnt(3)
	v_bfe_u32 v2, v34, 16, 1
	v_add3_u32 v2, v34, v2, s37
	v_bfe_u32 v19, v35, 16, 1
	v_lshrrev_b32_e32 v2, 16, v2
	v_add3_u32 v19, v35, v19, s37
	v_and_or_b32 v34, v19, s38, v2
	s_waitcnt lgkmcnt(2)
	v_bfe_u32 v2, v30, 16, 1
	v_add3_u32 v2, v30, v2, s37
	v_bfe_u32 v19, v31, 16, 1
	v_lshrrev_b32_e32 v2, 16, v2
	v_add3_u32 v19, v31, v19, s37
	v_and_or_b32 v35, v19, s38, v2
	s_waitcnt lgkmcnt(1)
	v_bfe_u32 v2, v28, 16, 1
	v_add3_u32 v2, v28, v2, s37
	v_bfe_u32 v19, v29, 16, 1
	v_lshrrev_b32_e32 v2, 16, v2
	v_add3_u32 v19, v29, v19, s37
	v_and_or_b32 v36, v19, s38, v2
	s_waitcnt lgkmcnt(0)
	v_bfe_u32 v2, v26, 16, 1
	v_add3_u32 v2, v26, v2, s37
	v_bfe_u32 v19, v27, 16, 1
	v_ashrrev_i32_e32 v33, 31, v32
	v_lshrrev_b32_e32 v2, 16, v2
	v_add3_u32 v19, v27, v19, s37
	v_lshlrev_b64 v[26:27], 10, v[32:33]
	v_and_or_b32 v37, v19, s38, v2
	v_lshl_add_u64 v[26:27], v[24:25], 0, v[26:27]
	global_store_dwordx4 v[26:27], v[34:37], off
	ds_read2_b32 v[34:35], v42 offset0:16 offset1:49
	ds_read2_b32 v[30:31], v42 offset0:82 offset1:115
	ds_read2_b32 v[28:29], v42 offset0:148 offset1:181
	ds_read2_b32 v[26:27], v42 offset0:214 offset1:247
	v_add_u32_e32 v2, s2, v44
	v_mul_hi_i32 v19, v2, s41
	v_lshrrev_b32_e32 v21, 31, v19
	v_ashrrev_i32_e32 v19, 5, v19
	v_add_u32_e32 v19, v19, v21
	v_mul_lo_u32 v21, v19, s42
	v_sub_u32_e32 v2, v2, v21
	v_cmp_lt_i32_e32 vcc, s43, v2
	s_and_saveexec_b64 s[8:9], vcc
	s_xor_b64 s[8:9], exec, s[8:9]
	v_and_b32_e32 v21, 0x7fffffe0, v2
	v_lshl_add_u32 v19, v19, 6, v21
	v_and_or_b32 v19, v2, 3, v19
	v_lshlrev_b32_e32 v21, 1, v2
	v_lshrrev_b32_e32 v2, 2, v2
	v_and_b32_e32 v21, 24, v21
	v_and_b32_e32 v2, 4, v2
	v_or3_b32 v2, v19, v21, v2
	v_add_u32_e32 v32, 0x180, v2
	s_andn2_saveexec_b64 s[8:9], s[8:9]
	v_lshl_add_u32 v32, v19, 7, v2
	s_or_b64 exec, exec, s[8:9]
	s_waitcnt lgkmcnt(3)
	v_bfe_u32 v2, v34, 16, 1
	v_add3_u32 v2, v34, v2, s37
	v_bfe_u32 v19, v35, 16, 1
	v_lshrrev_b32_e32 v2, 16, v2
	v_add3_u32 v19, v35, v19, s37
	v_and_or_b32 v34, v19, s38, v2
	s_waitcnt lgkmcnt(2)
	v_bfe_u32 v2, v30, 16, 1
	v_add3_u32 v2, v30, v2, s37
	v_bfe_u32 v19, v31, 16, 1
	v_lshrrev_b32_e32 v2, 16, v2
	v_add3_u32 v19, v31, v19, s37
	v_and_or_b32 v35, v19, s38, v2
	s_waitcnt lgkmcnt(1)
	v_bfe_u32 v2, v28, 16, 1
	v_add3_u32 v2, v28, v2, s37
	v_bfe_u32 v19, v29, 16, 1
	v_lshrrev_b32_e32 v2, 16, v2
	v_add3_u32 v19, v29, v19, s37
	v_and_or_b32 v36, v19, s38, v2
	s_waitcnt lgkmcnt(0)
	v_bfe_u32 v2, v26, 16, 1
	v_add3_u32 v2, v26, v2, s37
	v_bfe_u32 v19, v27, 16, 1
	v_ashrrev_i32_e32 v33, 31, v32
	v_lshrrev_b32_e32 v2, 16, v2
	v_add3_u32 v19, v27, v19, s37
	v_lshlrev_b64 v[26:27], 10, v[32:33]
	v_and_or_b32 v37, v19, s38, v2
	v_lshl_add_u64 v[26:27], v[24:25], 0, v[26:27]
	global_store_dwordx4 v[26:27], v[34:37], off
	ds_read2_b32 v[34:35], v42 offset0:24 offset1:57
	ds_read2_b32 v[32:33], v42 offset0:90 offset1:123
	ds_read2_b32 v[28:29], v42 offset0:156 offset1:189
	ds_read2_b32 v[26:27], v42 offset0:222 offset1:255
	v_add_u32_e32 v2, s2, v45
	v_mul_hi_i32 v19, v2, s41
	v_lshrrev_b32_e32 v21, 31, v19
	v_ashrrev_i32_e32 v19, 5, v19
	v_add_u32_e32 v19, v19, v21
	v_mul_lo_u32 v21, v19, s42
	v_sub_u32_e32 v2, v2, v21
	v_cmp_lt_i32_e32 vcc, s43, v2
	s_and_saveexec_b64 s[8:9], vcc
	s_xor_b64 s[8:9], exec, s[8:9]
	v_and_b32_e32 v21, 0x7fffffe0, v2
	v_lshl_add_u32 v19, v19, 6, v21
	v_and_or_b32 v19, v2, 3, v19
	v_lshlrev_b32_e32 v21, 1, v2
	v_lshrrev_b32_e32 v2, 2, v2
	v_and_b32_e32 v21, 24, v21
	v_and_b32_e32 v2, 4, v2
	v_or3_b32 v2, v19, v21, v2
	v_add_u32_e32 v30, 0x180, v2
	s_andn2_saveexec_b64 s[8:9], s[8:9]
	v_lshl_add_u32 v30, v19, 7, v2
	s_or_b64 exec, exec, s[8:9]
	s_waitcnt lgkmcnt(3)
	v_bfe_u32 v19, v34, 16, 1
	v_bfe_u32 v2, v35, 16, 1
	v_add3_u32 v19, v34, v19, s37
	v_add3_u32 v2, v35, v2, s37
	v_lshrrev_b32_e32 v19, 16, v19
	v_and_or_b32 v34, v2, s38, v19
	s_waitcnt lgkmcnt(2)
	v_bfe_u32 v19, v32, 16, 1
	v_bfe_u32 v2, v33, 16, 1
	v_add3_u32 v19, v32, v19, s37
	v_add3_u32 v2, v33, v2, s37
	v_lshrrev_b32_e32 v19, 16, v19
	v_and_or_b32 v35, v2, s38, v19
	s_waitcnt lgkmcnt(1)
	v_bfe_u32 v19, v28, 16, 1
	v_bfe_u32 v2, v29, 16, 1
	v_add3_u32 v19, v28, v19, s37
	v_add3_u32 v2, v29, v2, s37
	v_lshrrev_b32_e32 v19, 16, v19
	v_and_or_b32 v36, v2, s38, v19
	s_waitcnt lgkmcnt(0)
	v_bfe_u32 v19, v26, 16, 1
	v_bfe_u32 v2, v27, 16, 1
	v_add3_u32 v19, v26, v19, s37
	v_ashrrev_i32_e32 v31, 31, v30
	v_add3_u32 v2, v27, v2, s37
	v_lshrrev_b32_e32 v19, 16, v19
	v_lshlrev_b64 v[26:27], 10, v[30:31]
	v_and_or_b32 v37, v2, s38, v19
	v_lshl_add_u64 v[24:25], v[24:25], 0, v[26:27]
	global_store_dwordx4 v[24:25], v[34:37], off
	s_waitcnt lgkmcnt(0)

.LBB0_47:
	s_lshl_b32 s17, s9, 1
	s_lshl_b32 s56, s8, 1
	v_add_u32_e32 v48, s17, v2
	v_add_u32_e32 v50, s56, v19
	v_add_u32_e32 v52, s17, v26
	v_add_u32_e32 v54, s56, v21
	v_add_u32_e32 v56, s17, v28
	v_add_u32_e32 v58, s56, v23
	v_add_u32_e32 v60, s17, v30
	v_add_u32_e32 v62, s56, v27
	v_add_u32_e32 v64, s17, v32
	v_add_u32_e32 v66, s56, v29
	v_add_u32_e32 v68, s17, v34
	v_add_u32_e32 v70, s56, v31
	v_add_u32_e32 v72, s17, v36
	v_add_u32_e32 v74, s56, v33
	v_add_u32_e32 v76, s17, v38
	v_add_u32_e32 v78, s56, v35
	v_ashrrev_i32_e32 v49, 31, v48
	v_ashrrev_i32_e32 v51, 31, v50
	v_ashrrev_i32_e32 v53, 31, v52
	v_ashrrev_i32_e32 v55, 31, v54
	v_ashrrev_i32_e32 v57, 31, v56
	v_ashrrev_i32_e32 v59, 31, v58
	v_ashrrev_i32_e32 v61, 31, v60
	v_ashrrev_i32_e32 v63, 31, v62
	v_ashrrev_i32_e32 v65, 31, v64
	v_ashrrev_i32_e32 v67, 31, v66
	v_ashrrev_i32_e32 v69, 31, v68
	v_ashrrev_i32_e32 v71, 31, v70
	v_ashrrev_i32_e32 v73, 31, v72
	v_ashrrev_i32_e32 v75, 31, v74
	v_ashrrev_i32_e32 v77, 31, v76
	v_ashrrev_i32_e32 v79, 31, v78
	v_lshlrev_b64 v[48:49], 13, v[48:49]
	v_lshlrev_b64 v[50:51], 13, v[50:51]
	v_lshlrev_b64 v[52:53], 13, v[52:53]
	v_lshlrev_b64 v[54:55], 13, v[54:55]
	v_lshlrev_b64 v[56:57], 13, v[56:57]
	v_lshlrev_b64 v[58:59], 13, v[58:59]
	v_lshlrev_b64 v[60:61], 13, v[60:61]
	v_lshlrev_b64 v[62:63], 13, v[62:63]
	v_lshlrev_b64 v[64:65], 13, v[64:65]
	v_lshlrev_b64 v[66:67], 13, v[66:67]
	v_lshlrev_b64 v[68:69], 13, v[68:69]
	v_lshlrev_b64 v[70:71], 13, v[70:71]
	v_lshlrev_b64 v[72:73], 13, v[72:73]
	v_lshlrev_b64 v[74:75], 13, v[74:75]
	v_lshlrev_b64 v[76:77], 13, v[76:77]
	v_lshlrev_b64 v[78:79], 13, v[78:79]
	v_lshl_add_u64 v[48:49], v[24:25], 0, v[48:49]
	v_lshl_add_u64 v[50:51], v[24:25], 0, v[50:51]
	v_lshl_add_u64 v[52:53], v[24:25], 0, v[52:53]
	v_lshl_add_u64 v[54:55], v[24:25], 0, v[54:55]
	v_lshl_add_u64 v[56:57], v[24:25], 0, v[56:57]
	v_lshl_add_u64 v[58:59], v[24:25], 0, v[58:59]
	v_lshl_add_u64 v[60:61], v[24:25], 0, v[60:61]
	v_lshl_add_u64 v[62:63], v[24:25], 0, v[62:63]
	v_lshl_add_u64 v[64:65], v[24:25], 0, v[64:65]
	v_lshl_add_u64 v[66:67], v[24:25], 0, v[66:67]
	v_lshl_add_u64 v[68:69], v[24:25], 0, v[68:69]
	v_lshl_add_u64 v[70:71], v[24:25], 0, v[70:71]
	v_lshl_add_u64 v[72:73], v[24:25], 0, v[72:73]
	v_lshl_add_u64 v[74:75], v[24:25], 0, v[74:75]
	v_lshl_add_u64 v[76:77], v[24:25], 0, v[76:77]
	v_lshl_add_u64 v[78:79], v[24:25], 0, v[78:79]
	global_load_dword v37, v[48:49], off nt
	global_load_dword v40, v[50:51], off nt
	global_load_dword v47, v[52:53], off nt
	global_load_dword v80, v[54:55], off nt
	global_load_dword v81, v[56:57], off nt
	global_load_dword v82, v[58:59], off nt
	global_load_dword v83, v[60:61], off nt
	global_load_dword v84, v[62:63], off nt
	global_load_dword v85, v[64:65], off nt
	global_load_dword v86, v[66:67], off nt
	global_load_dword v87, v[68:69], off nt
	global_load_dword v88, v[70:71], off nt
	global_load_dword v89, v[72:73], off nt
	global_load_dword v90, v[74:75], off nt
	global_load_dword v91, v[76:77], off nt
	global_load_dword v92, v[78:79], off nt
	s_add_i32 s9, s9, 16
	s_add_i32 s8, s8, 16
	s_add_i32 s16, s16, -16
	v_add_u32_e32 v48, s17, v0
	v_add_u32_e32 v50, s56, v1
	v_add_u32_e32 v52, s17, v8
	v_add_u32_e32 v54, s56, v5
	v_add_u32_e32 v56, s17, v10
	v_add_u32_e32 v58, s56, v7
	v_add_u32_e32 v60, s17, v12
	v_add_u32_e32 v62, s56, v9
	v_add_u32_e32 v64, s17, v14
	v_add_u32_e32 v66, s56, v11
	v_add_u32_e32 v68, s17, v16
	v_add_u32_e32 v70, s56, v13
	v_add_u32_e32 v72, s17, v18
	v_add_u32_e32 v74, s56, v15
	v_add_u32_e32 v76, s17, v20
	v_add_u32_e32 v78, s56, v17
	s_cmp_lg_u32 s16, 0
	v_mad_u64_u32 v[48:49], s[56:57], v48, s35, v[4:5]
	v_mad_u64_u32 v[50:51], s[56:57], v50, s35, v[4:5]
	v_mad_u64_u32 v[52:53], s[56:57], v52, s35, v[4:5]
	v_mad_u64_u32 v[54:55], s[56:57], v54, s35, v[4:5]
	v_mad_u64_u32 v[56:57], s[56:57], v56, s35, v[4:5]
	v_mad_u64_u32 v[58:59], s[56:57], v58, s35, v[4:5]
	v_mad_u64_u32 v[60:61], s[56:57], v60, s35, v[4:5]
	v_mad_u64_u32 v[62:63], s[56:57], v62, s35, v[4:5]
	v_mad_u64_u32 v[64:65], s[56:57], v64, s35, v[4:5]
	v_mad_u64_u32 v[66:67], s[56:57], v66, s35, v[4:5]
	v_mad_u64_u32 v[68:69], s[56:57], v68, s35, v[4:5]
	v_mad_u64_u32 v[70:71], s[56:57], v70, s35, v[4:5]
	v_mad_u64_u32 v[72:73], s[56:57], v72, s35, v[4:5]
	v_mad_u64_u32 v[74:75], s[56:57], v74, s35, v[4:5]
	v_mad_u64_u32 v[76:77], s[56:57], v76, s35, v[4:5]
	v_mad_u64_u32 v[78:79], s[56:57], v78, s35, v[4:5]
	s_waitcnt vmcnt(15)
	ds_write_b32 v48, v37
	s_waitcnt vmcnt(14)
	ds_write_b32 v50, v40
	s_waitcnt vmcnt(13)
	ds_write_b32 v52, v47
	s_waitcnt vmcnt(12)
	ds_write_b32 v54, v80
	s_waitcnt vmcnt(11)
	ds_write_b32 v56, v81
	s_waitcnt vmcnt(10)
	ds_write_b32 v58, v82
	s_waitcnt vmcnt(9)
	ds_write_b32 v60, v83
	s_waitcnt vmcnt(8)
	ds_write_b32 v62, v84
	s_waitcnt vmcnt(7)
	ds_write_b32 v64, v85
	s_waitcnt vmcnt(6)
	ds_write_b32 v66, v86
	s_waitcnt vmcnt(5)
	ds_write_b32 v68, v87
	s_waitcnt vmcnt(4)
	ds_write_b32 v70, v88
	s_waitcnt vmcnt(3)
	ds_write_b32 v72, v89
	s_waitcnt vmcnt(2)
	ds_write_b32 v74, v90
	s_waitcnt vmcnt(1)
	ds_write_b32 v76, v91
	s_waitcnt vmcnt(0)
	ds_write_b32 v78, v92
	s_cbranch_scc1 .LBB0_47
	s_waitcnt lgkmcnt(0)
	s_mul_i32 s9, s6, 0x1600000
	ds_read2_b32 v[28:29], v42 offset1:8
	s_mul_hi_i32 s8, s6, 0x1600000
	s_add_u32 s9, s23, s9
	ds_read2_b32 v[32:33], v42 offset0:33 offset1:41
	s_addc_u32 s16, s24, s8
	s_lshl_b32 s7, s7, 1
	s_add_u32 s8, s9, s7
	ds_read2_b32 v[34:35], v42 offset0:66 offset1:74
	s_addc_u32 s9, s16, 0
	v_lshlrev_b32_e32 v2, 1, v6
	ds_read2_b32 v[36:37], v42 offset0:99 offset1:107
	v_lshl_add_u64 v[30:31], s[8:9], 0, v[2:3]
	s_waitcnt lgkmcnt(3)
	v_bfe_u32 v2, v28, 16, 1
	v_add3_u32 v2, v28, v2, s37
	s_waitcnt lgkmcnt(2)
	v_bfe_u32 v19, v32, 16, 1
	ds_read2_b32 v[48:49], v42 offset0:132 offset1:140
	v_lshrrev_b32_e32 v2, 16, v2
	v_add3_u32 v19, v32, v19, s37
	ds_read2_b32 v[50:51], v42 offset0:165 offset1:173
	v_and_or_b32 v24, v19, s38, v2
	s_waitcnt lgkmcnt(3)
	v_bfe_u32 v2, v34, 16, 1
	v_add3_u32 v2, v34, v2, s37
	s_waitcnt lgkmcnt(2)
	v_bfe_u32 v19, v36, 16, 1
	ds_read2_b32 v[52:53], v42 offset0:198 offset1:206
	v_lshrrev_b32_e32 v2, 16, v2
	v_add3_u32 v19, v36, v19, s37
	ds_read2_b32 v[54:55], v42 offset0:231 offset1:239
	v_and_or_b32 v25, v19, s38, v2
	s_waitcnt lgkmcnt(3)
	v_bfe_u32 v2, v48, 16, 1
	v_add3_u32 v2, v48, v2, s37
	s_waitcnt lgkmcnt(2)
	v_bfe_u32 v19, v50, 16, 1
	v_lshrrev_b32_e32 v2, 16, v2
	v_add3_u32 v19, v50, v19, s37
	v_and_or_b32 v26, v19, s38, v2
	s_waitcnt lgkmcnt(1)
	v_bfe_u32 v2, v52, 16, 1
	v_add3_u32 v2, v52, v2, s37
	s_waitcnt lgkmcnt(0)
	v_bfe_u32 v19, v54, 16, 1
	v_lshrrev_b32_e32 v2, 16, v2
	v_add3_u32 v19, v54, v19, s37
	v_and_or_b32 v27, v19, s38, v2
	v_add_u32_e32 v2, s2, v41
	v_mad_i64_i32 v[56:57], s[8:9], v2, s45, v[30:31]
	v_bfe_u32 v2, v29, 16, 1
	v_add3_u32 v2, v29, v2, s37
	v_bfe_u32 v19, v33, 16, 1
	v_lshrrev_b32_e32 v2, 16, v2
	v_add3_u32 v19, v33, v19, s37
	global_store_dwordx4 v[56:57], v[24:27], off
	ds_read2_b32 v[28:29], v42 offset0:16 offset1:24
	s_waitcnt lgkmcnt(0)
	v_bfe_u32 v21, v29, 16, 1
	v_and_or_b32 v24, v19, s38, v2
	v_bfe_u32 v2, v35, 16, 1
	v_add3_u32 v2, v35, v2, s37
	v_bfe_u32 v19, v37, 16, 1
	v_lshrrev_b32_e32 v2, 16, v2
	v_add3_u32 v19, v37, v19, s37
	v_and_or_b32 v25, v19, s38, v2
	v_bfe_u32 v2, v49, 16, 1
	v_add3_u32 v2, v49, v2, s37
	v_bfe_u32 v19, v51, 16, 1
	v_lshrrev_b32_e32 v2, 16, v2
	v_add3_u32 v19, v51, v19, s37
	v_and_or_b32 v26, v19, s38, v2
	v_bfe_u32 v2, v53, 16, 1
	v_add3_u32 v2, v53, v2, s37
	v_bfe_u32 v19, v55, 16, 1
	v_lshrrev_b32_e32 v2, 16, v2
	v_add3_u32 v19, v55, v19, s37
	v_and_or_b32 v27, v19, s38, v2
	v_add_u32_e32 v2, s2, v43
	v_mad_i64_i32 v[32:33], s[8:9], v2, s45, v[30:31]
	global_store_dwordx4 v[32:33], v[24:27], off
	ds_read2_b32 v[32:33], v42 offset0:49 offset1:57
	ds_read2_b32 v[34:35], v42 offset0:82 offset1:90
	ds_read2_b32 v[36:37], v42 offset0:115 offset1:123
	v_bfe_u32 v2, v28, 16, 1
	v_add3_u32 v2, v28, v2, s37
	s_waitcnt lgkmcnt(2)
	v_bfe_u32 v19, v32, 16, 1
	ds_read2_b32 v[48:49], v42 offset0:148 offset1:156
	v_lshrrev_b32_e32 v2, 16, v2
	v_add3_u32 v19, v32, v19, s37
	ds_read2_b32 v[50:51], v42 offset0:181 offset1:189
	v_and_or_b32 v24, v19, s38, v2
	s_waitcnt lgkmcnt(3)
	v_bfe_u32 v2, v34, 16, 1
	v_add3_u32 v2, v34, v2, s37
	s_waitcnt lgkmcnt(2)
	v_bfe_u32 v19, v36, 16, 1
	ds_read2_b32 v[52:53], v42 offset0:214 offset1:222
	v_lshrrev_b32_e32 v2, 16, v2
	v_add3_u32 v19, v36, v19, s37
	ds_read2_b32 v[54:55], v42 offset0:247 offset1:255
	v_and_or_b32 v25, v19, s38, v2
	s_waitcnt lgkmcnt(3)
	v_bfe_u32 v2, v48, 16, 1
	v_add3_u32 v2, v48, v2, s37
	s_waitcnt lgkmcnt(2)
	v_bfe_u32 v19, v50, 16, 1
	v_lshrrev_b32_e32 v2, 16, v2
	v_add3_u32 v19, v50, v19, s37
	v_and_or_b32 v26, v19, s38, v2
	s_waitcnt lgkmcnt(1)
	v_bfe_u32 v2, v52, 16, 1
	v_add3_u32 v2, v52, v2, s37
	s_waitcnt lgkmcnt(0)
	v_bfe_u32 v19, v54, 16, 1
	v_lshrrev_b32_e32 v2, 16, v2
	v_add3_u32 v19, v54, v19, s37
	v_and_or_b32 v27, v19, s38, v2
	v_add_u32_e32 v2, s2, v44
	v_bfe_u32 v19, v33, 16, 1
	v_add3_u32 v21, v29, v21, s37
	v_mad_i64_i32 v[56:57], s[8:9], v2, s45, v[30:31]
	v_add3_u32 v19, v33, v19, s37
	v_lshrrev_b32_e32 v21, 16, v21
	global_store_dwordx4 v[56:57], v[24:27], off
	v_add_u32_e32 v2, s2, v45
	v_mad_i64_i32 v[28:29], s[8:9], v2, s45, v[30:31]
	v_and_or_b32 v24, v19, s38, v21
	v_bfe_u32 v21, v35, 16, 1
	v_bfe_u32 v19, v37, 16, 1
	v_add3_u32 v21, v35, v21, s37
	v_add3_u32 v19, v37, v19, s37
	v_lshrrev_b32_e32 v21, 16, v21
	v_and_or_b32 v25, v19, s38, v21
	v_bfe_u32 v21, v49, 16, 1
	v_bfe_u32 v19, v51, 16, 1
	v_add3_u32 v21, v49, v21, s37
	v_add3_u32 v19, v51, v19, s37
	v_lshrrev_b32_e32 v21, 16, v21
	v_and_or_b32 v26, v19, s38, v21
	v_bfe_u32 v21, v53, 16, 1
	v_bfe_u32 v19, v55, 16, 1
	v_add3_u32 v21, v53, v21, s37
	v_add3_u32 v19, v55, v19, s37
	v_lshrrev_b32_e32 v21, 16, v21
	v_and_or_b32 v27, v19, s38, v21
	global_store_dwordx4 v[28:29], v[24:27], off
	s_waitcnt lgkmcnt(0)

.LBB0_52:
	s_lshl_b32 s17, s9, 1
	s_lshl_b32 s58, s8, 1
	v_add_u32_e32 v37, s17, v2
	v_add_u32_e32 v40, s58, v19
	v_add_u32_e32 v47, s17, v26
	v_add_u32_e32 v54, s58, v21
	v_add_u32_e32 v56, s17, v28
	v_add_u32_e32 v58, s58, v23
	v_add_u32_e32 v60, s17, v30
	v_add_u32_e32 v62, s58, v27
	v_add_u32_e32 v64, s17, v32
	v_add_u32_e32 v66, s58, v29
	v_add_u32_e32 v68, s17, v34
	v_add_u32_e32 v70, s58, v31
	v_add_u32_e32 v72, s17, v36
	v_add_u32_e32 v74, s58, v33
	v_add_u32_e32 v76, s17, v38
	v_add_u32_e32 v78, s58, v35
	v_mad_i64_i32 v[48:49], s[56:57], v37, s47, v[24:25]
	v_mad_i64_i32 v[50:51], s[56:57], v40, s47, v[24:25]
	v_mad_i64_i32 v[52:53], s[56:57], v47, s47, v[24:25]
	v_mad_i64_i32 v[54:55], s[56:57], v54, s47, v[24:25]
	v_mad_i64_i32 v[56:57], s[56:57], v56, s47, v[24:25]
	v_mad_i64_i32 v[58:59], s[56:57], v58, s47, v[24:25]
	v_mad_i64_i32 v[60:61], s[56:57], v60, s47, v[24:25]
	v_mad_i64_i32 v[62:63], s[56:57], v62, s47, v[24:25]
	v_mad_i64_i32 v[64:65], s[56:57], v64, s47, v[24:25]
	v_mad_i64_i32 v[66:67], s[56:57], v66, s47, v[24:25]
	v_mad_i64_i32 v[68:69], s[56:57], v68, s47, v[24:25]
	v_mad_i64_i32 v[70:71], s[56:57], v70, s47, v[24:25]
	v_mad_i64_i32 v[72:73], s[56:57], v72, s47, v[24:25]
	v_mad_i64_i32 v[74:75], s[56:57], v74, s47, v[24:25]
	v_mad_i64_i32 v[76:77], s[56:57], v76, s47, v[24:25]
	v_mad_i64_i32 v[78:79], s[56:57], v78, s47, v[24:25]
	global_load_dword v37, v[48:49], off nt
	global_load_dword v40, v[50:51], off nt
	global_load_dword v47, v[52:53], off nt
	global_load_dword v80, v[54:55], off nt
	global_load_dword v81, v[56:57], off nt
	global_load_dword v82, v[58:59], off nt
	global_load_dword v83, v[60:61], off nt
	global_load_dword v84, v[62:63], off nt
	global_load_dword v85, v[64:65], off nt
	global_load_dword v86, v[66:67], off nt
	global_load_dword v87, v[68:69], off nt
	global_load_dword v88, v[70:71], off nt
	global_load_dword v89, v[72:73], off nt
	global_load_dword v90, v[74:75], off nt
	global_load_dword v91, v[76:77], off nt
	global_load_dword v92, v[78:79], off nt
	s_add_i32 s9, s9, 16
	s_add_i32 s8, s8, 16
	s_add_i32 s16, s16, -16
	v_add_u32_e32 v48, s17, v0
	v_add_u32_e32 v50, s58, v1
	v_add_u32_e32 v52, s17, v8
	v_add_u32_e32 v54, s58, v5
	v_add_u32_e32 v56, s17, v10
	v_add_u32_e32 v58, s58, v7
	v_add_u32_e32 v60, s17, v12
	v_add_u32_e32 v62, s58, v9
	v_add_u32_e32 v64, s17, v14
	v_add_u32_e32 v66, s58, v11
	v_add_u32_e32 v68, s17, v16
	v_add_u32_e32 v70, s58, v13
	v_add_u32_e32 v72, s17, v18
	v_add_u32_e32 v74, s58, v15
	v_add_u32_e32 v76, s17, v20
	v_add_u32_e32 v78, s58, v17
	s_cmp_lg_u32 s16, 0
	v_mad_u64_u32 v[48:49], s[56:57], v48, s35, v[4:5]
	v_mad_u64_u32 v[50:51], s[56:57], v50, s35, v[4:5]
	v_mad_u64_u32 v[52:53], s[56:57], v52, s35, v[4:5]
	v_mad_u64_u32 v[54:55], s[56:57], v54, s35, v[4:5]
	v_mad_u64_u32 v[56:57], s[56:57], v56, s35, v[4:5]
	v_mad_u64_u32 v[58:59], s[56:57], v58, s35, v[4:5]
	v_mad_u64_u32 v[60:61], s[56:57], v60, s35, v[4:5]
	v_mad_u64_u32 v[62:63], s[56:57], v62, s35, v[4:5]
	v_mad_u64_u32 v[64:65], s[56:57], v64, s35, v[4:5]
	v_mad_u64_u32 v[66:67], s[56:57], v66, s35, v[4:5]
	v_mad_u64_u32 v[68:69], s[56:57], v68, s35, v[4:5]
	v_mad_u64_u32 v[70:71], s[56:57], v70, s35, v[4:5]
	v_mad_u64_u32 v[72:73], s[56:57], v72, s35, v[4:5]
	v_mad_u64_u32 v[74:75], s[56:57], v74, s35, v[4:5]
	v_mad_u64_u32 v[76:77], s[56:57], v76, s35, v[4:5]
	v_mad_u64_u32 v[78:79], s[56:57], v78, s35, v[4:5]
	s_waitcnt vmcnt(15)
	ds_write_b32 v48, v37
	s_waitcnt vmcnt(14)
	ds_write_b32 v50, v40
	s_waitcnt vmcnt(13)
	ds_write_b32 v52, v47
	s_waitcnt vmcnt(12)
	ds_write_b32 v54, v80
	s_waitcnt vmcnt(11)
	ds_write_b32 v56, v81
	s_waitcnt vmcnt(10)
	ds_write_b32 v58, v82
	s_waitcnt vmcnt(9)
	ds_write_b32 v60, v83
	s_waitcnt vmcnt(8)
	ds_write_b32 v62, v84
	s_waitcnt vmcnt(7)
	ds_write_b32 v64, v85
	s_waitcnt vmcnt(6)
	ds_write_b32 v66, v86
	s_waitcnt vmcnt(5)
	ds_write_b32 v68, v87
	s_waitcnt vmcnt(4)
	ds_write_b32 v70, v88
	s_waitcnt vmcnt(3)
	ds_write_b32 v72, v89
	s_waitcnt vmcnt(2)
	ds_write_b32 v74, v90
	s_waitcnt vmcnt(1)
	ds_write_b32 v76, v91
	s_waitcnt vmcnt(0)
	ds_write_b32 v78, v92
	s_cbranch_scc1 .LBB0_52
	s_waitcnt lgkmcnt(0)
	s_mul_i32 s9, s6, 0x2c00000
	s_mul_hi_i32 s8, s6, 0x2c00000
	s_add_u32 s9, s25, s9
	ds_read2_b32 v[28:29], v42 offset1:8
	s_addc_u32 s16, s26, s8
	s_and_b32 s2, 0xffff, s2
	ds_read2_b32 v[32:33], v42 offset0:33 offset1:41
	s_and_b32 s7, 0xffff, s7
	s_lshl_b32 s2, s2, 1
	s_add_u32 s8, s9, s2
	ds_read2_b32 v[34:35], v42 offset0:66 offset1:74
	s_addc_u32 s9, s16, 0
	v_lshlrev_b32_e32 v2, 1, v6
	ds_read2_b32 v[36:37], v42 offset0:99 offset1:107
	v_lshl_add_u64 v[30:31], s[8:9], 0, v[2:3]
	s_waitcnt lgkmcnt(3)
	v_bfe_u32 v2, v28, 16, 1
	v_add3_u32 v2, v28, v2, s37
	s_waitcnt lgkmcnt(2)
	v_bfe_u32 v19, v32, 16, 1
	ds_read2_b32 v[48:49], v42 offset0:132 offset1:140
	v_lshrrev_b32_e32 v2, 16, v2
	v_add3_u32 v19, v32, v19, s37
	ds_read2_b32 v[50:51], v42 offset0:165 offset1:173
	v_and_or_b32 v24, v19, s38, v2
	s_waitcnt lgkmcnt(3)
	v_bfe_u32 v2, v34, 16, 1
	v_add3_u32 v2, v34, v2, s37
	s_waitcnt lgkmcnt(2)
	v_bfe_u32 v19, v36, 16, 1
	ds_read2_b32 v[52:53], v42 offset0:198 offset1:206
	v_lshrrev_b32_e32 v2, 16, v2
	v_add3_u32 v19, v36, v19, s37
	ds_read2_b32 v[54:55], v42 offset0:231 offset1:239
	v_and_or_b32 v25, v19, s38, v2
	s_waitcnt lgkmcnt(3)
	v_bfe_u32 v2, v48, 16, 1
	v_add3_u32 v2, v48, v2, s37
	s_waitcnt lgkmcnt(2)
	v_bfe_u32 v19, v50, 16, 1
	v_lshrrev_b32_e32 v2, 16, v2
	v_add3_u32 v19, v50, v19, s37
	v_and_or_b32 v26, v19, s38, v2
	s_waitcnt lgkmcnt(1)
	v_bfe_u32 v2, v52, 16, 1
	v_add3_u32 v2, v52, v2, s37
	s_waitcnt lgkmcnt(0)
	v_bfe_u32 v19, v54, 16, 1
	v_lshrrev_b32_e32 v2, 16, v2
	v_add3_u32 v19, v54, v19, s37
	v_and_or_b32 v27, v19, s38, v2
	v_add_u32_e32 v2, s7, v41
	v_mul_hi_i32 v19, v2, s48
	v_lshrrev_b32_e32 v21, 31, v19
	v_ashrrev_i32_e32 v19, 10, v19
	v_add_u32_e32 v19, v19, v21
	v_mul_i32_i24_e32 v21, 0x1600, v19
	v_sub_u32_e32 v21, v2, v21
	v_ashrrev_i16_e32 v23, 15, v21
	v_lshrrev_b16_e32 v23, 9, v23
	v_add_u16_e32 v21, v21, v23
	v_ashrrev_i32_e32 v23, 31, v2
	v_lshrrev_b32_e32 v23, 25, v23
	v_add_u32_e32 v23, v2, v23
	v_ashrrev_i16_e32 v21, 7, v21
	v_and_b32_e32 v23, 0xffffff80, v23
	v_lshlrev_b32_sdwa v21, v46, sext(v21) dst_sel:DWORD dst_unused:UNUSED_PAD src0_sel:DWORD src1_sel:WORD_0
	v_lshlrev_b32_e32 v19, 7, v19
	v_sub_u32_e32 v2, v2, v23
	v_add3_u32 v56, v19, v2, v21
	v_ashrrev_i32_e32 v57, 31, v56
	v_bfe_u32 v2, v29, 16, 1
	v_lshlrev_b64 v[56:57], 12, v[56:57]
	v_add3_u32 v2, v29, v2, s37
	v_bfe_u32 v19, v33, 16, 1
	v_lshl_add_u64 v[56:57], v[30:31], 0, v[56:57]
	v_lshrrev_b32_e32 v2, 16, v2
	v_add3_u32 v19, v33, v19, s37
	global_store_dwordx4 v[56:57], v[24:27], off
	ds_read2_b32 v[32:33], v42 offset0:16 offset1:24
	s_nop 0
	v_and_or_b32 v24, v19, s38, v2
	v_bfe_u32 v2, v35, 16, 1
	v_add3_u32 v2, v35, v2, s37
	v_bfe_u32 v19, v37, 16, 1
	v_lshrrev_b32_e32 v2, 16, v2
	v_add3_u32 v19, v37, v19, s37
	v_and_or_b32 v25, v19, s38, v2
	v_bfe_u32 v2, v49, 16, 1
	v_add3_u32 v2, v49, v2, s37
	v_bfe_u32 v19, v51, 16, 1
	v_lshrrev_b32_e32 v2, 16, v2
	v_add3_u32 v19, v51, v19, s37
	v_and_or_b32 v26, v19, s38, v2
	v_bfe_u32 v2, v53, 16, 1
	v_add3_u32 v2, v53, v2, s37
	v_bfe_u32 v19, v55, 16, 1
	v_lshrrev_b32_e32 v2, 16, v2
	v_add3_u32 v19, v55, v19, s37
	v_and_or_b32 v27, v19, s38, v2
	v_add_u32_e32 v2, s7, v43
	v_mul_hi_i32 v19, v2, s48
	v_lshrrev_b32_e32 v21, 31, v19
	v_ashrrev_i32_e32 v19, 10, v19
	v_add_u32_e32 v19, v19, v21
	v_mul_i32_i24_e32 v21, 0x1600, v19
	v_sub_u32_e32 v21, v2, v21
	v_ashrrev_i16_e32 v23, 15, v21
	v_lshrrev_b16_e32 v23, 9, v23
	v_add_u16_e32 v21, v21, v23
	v_ashrrev_i32_e32 v23, 31, v2
	v_lshrrev_b32_e32 v23, 25, v23
	v_add_u32_e32 v23, v2, v23
	v_ashrrev_i16_e32 v21, 7, v21
	v_and_b32_e32 v23, 0xffffff80, v23
	v_lshlrev_b32_sdwa v21, v46, sext(v21) dst_sel:DWORD dst_unused:UNUSED_PAD src0_sel:DWORD src1_sel:WORD_0
	v_lshlrev_b32_e32 v19, 7, v19
	v_sub_u32_e32 v2, v2, v23
	v_add3_u32 v28, v19, v2, v21
	v_ashrrev_i32_e32 v29, 31, v28
	v_lshlrev_b64 v[28:29], 12, v[28:29]
	v_lshl_add_u64 v[28:29], v[30:31], 0, v[28:29]
	global_store_dwordx4 v[28:29], v[24:27], off
	ds_read2_b32 v[28:29], v42 offset0:49 offset1:57
	ds_read2_b32 v[34:35], v42 offset0:82 offset1:90
	ds_read2_b32 v[36:37], v42 offset0:115 offset1:123
	s_waitcnt lgkmcnt(3)
	v_bfe_u32 v2, v32, 16, 1
	v_add3_u32 v2, v32, v2, s37
	s_waitcnt lgkmcnt(2)
	v_bfe_u32 v19, v28, 16, 1
	ds_read2_b32 v[48:49], v42 offset0:148 offset1:156
	v_lshrrev_b32_e32 v2, 16, v2
	v_add3_u32 v19, v28, v19, s37
	ds_read2_b32 v[50:51], v42 offset0:181 offset1:189
	v_and_or_b32 v24, v19, s38, v2
	s_waitcnt lgkmcnt(3)
	v_bfe_u32 v2, v34, 16, 1
	v_add3_u32 v2, v34, v2, s37
	s_waitcnt lgkmcnt(2)
	v_bfe_u32 v19, v36, 16, 1
	ds_read2_b32 v[52:53], v42 offset0:214 offset1:222
	v_lshrrev_b32_e32 v2, 16, v2
	v_add3_u32 v19, v36, v19, s37
	ds_read2_b32 v[54:55], v42 offset0:247 offset1:255
	v_and_or_b32 v25, v19, s38, v2
	s_waitcnt lgkmcnt(3)
	v_bfe_u32 v2, v48, 16, 1
	v_add3_u32 v2, v48, v2, s37
	s_waitcnt lgkmcnt(2)
	v_bfe_u32 v19, v50, 16, 1
	v_lshrrev_b32_e32 v2, 16, v2
	v_add3_u32 v19, v50, v19, s37
	v_and_or_b32 v26, v19, s38, v2
	s_waitcnt lgkmcnt(1)
	v_bfe_u32 v2, v52, 16, 1
	v_add3_u32 v2, v52, v2, s37
	s_waitcnt lgkmcnt(0)
	v_bfe_u32 v19, v54, 16, 1
	v_lshrrev_b32_e32 v2, 16, v2
	v_add3_u32 v19, v54, v19, s37
	v_and_or_b32 v27, v19, s38, v2
	v_add_u32_e32 v2, s7, v44
	v_mul_hi_i32 v19, v2, s48
	v_lshrrev_b32_e32 v21, 31, v19
	v_ashrrev_i32_e32 v19, 10, v19
	v_add_u32_e32 v19, v19, v21
	v_mul_i32_i24_e32 v21, 0x1600, v19
	v_sub_u32_e32 v21, v2, v21
	v_ashrrev_i16_e32 v23, 15, v21
	v_lshrrev_b16_e32 v23, 9, v23
	v_add_u16_e32 v21, v21, v23
	v_ashrrev_i32_e32 v23, 31, v2
	v_lshrrev_b32_e32 v23, 25, v23
	v_add_u32_e32 v23, v2, v23
	v_ashrrev_i16_e32 v21, 7, v21
	v_and_b32_e32 v23, 0xffffff80, v23
	v_lshlrev_b32_sdwa v21, v46, sext(v21) dst_sel:DWORD dst_unused:UNUSED_PAD src0_sel:DWORD src1_sel:WORD_0
	v_lshlrev_b32_e32 v19, 7, v19
	v_sub_u32_e32 v2, v2, v23
	v_add3_u32 v56, v19, v2, v21
	v_add_u32_e32 v2, s7, v45
	v_mul_hi_i32 v19, v2, s48
	v_lshrrev_b32_e32 v21, 31, v19
	v_ashrrev_i32_e32 v19, 10, v19
	v_add_u32_e32 v19, v19, v21
	v_mul_i32_i24_e32 v21, 0x1600, v19
	v_sub_u32_e32 v21, v2, v21
	v_ashrrev_i16_e32 v23, 15, v21
	v_lshrrev_b16_e32 v23, 9, v23
	v_add_u16_e32 v21, v21, v23
	v_ashrrev_i32_e32 v23, 31, v2
	v_lshrrev_b32_e32 v23, 25, v23
	v_add_u32_e32 v23, v2, v23
	v_ashrrev_i16_e32 v21, 7, v21
	v_and_b32_e32 v23, 0xffffff80, v23
	v_lshlrev_b32_sdwa v21, v46, sext(v21) dst_sel:DWORD dst_unused:UNUSED_PAD src0_sel:DWORD src1_sel:WORD_0
	v_lshlrev_b32_e32 v19, 7, v19
	v_sub_u32_e32 v2, v2, v23
	v_ashrrev_i32_e32 v57, 31, v56
	v_add3_u32 v28, v19, v2, v21
	v_bfe_u32 v19, v33, 16, 1
	v_lshlrev_b64 v[56:57], 12, v[56:57]
	v_bfe_u32 v2, v29, 16, 1
	v_add3_u32 v19, v33, v19, s37
	v_lshl_add_u64 v[56:57], v[30:31], 0, v[56:57]
	v_add3_u32 v2, v29, v2, s37
	v_lshrrev_b32_e32 v19, 16, v19
	global_store_dwordx4 v[56:57], v[24:27], off
	v_ashrrev_i32_e32 v29, 31, v28
	v_lshlrev_b64 v[28:29], 12, v[28:29]
	v_and_or_b32 v24, v2, s38, v19
	v_bfe_u32 v19, v35, 16, 1
	v_bfe_u32 v2, v37, 16, 1
	v_add3_u32 v19, v35, v19, s37
	v_add3_u32 v2, v37, v2, s37
	v_lshrrev_b32_e32 v19, 16, v19
	v_and_or_b32 v25, v2, s38, v19
	v_bfe_u32 v19, v49, 16, 1
	v_bfe_u32 v2, v51, 16, 1
	v_add3_u32 v19, v49, v19, s37
	v_add3_u32 v2, v51, v2, s37
	v_lshrrev_b32_e32 v19, 16, v19
	v_and_or_b32 v26, v2, s38, v19
	v_bfe_u32 v19, v53, 16, 1
	v_bfe_u32 v2, v55, 16, 1
	v_add3_u32 v19, v53, v19, s37
	v_add3_u32 v2, v55, v2, s37
	v_lshrrev_b32_e32 v19, 16, v19
	v_and_or_b32 v27, v2, s38, v19
	v_lshl_add_u64 v[28:29], v[30:31], 0, v[28:29]
	global_store_dwordx4 v[28:29], v[24:27], off
	s_waitcnt lgkmcnt(0)

.LBB0_58:
	s_lshl_b32 s58, s56, 1
	s_lshl_b32 s59, s17, 1
	v_add_u32_e32 v48, s58, v2
	v_add_u32_e32 v50, s59, v19
	v_add_u32_e32 v52, s58, v28
	v_add_u32_e32 v54, s59, v21
	v_add_u32_e32 v56, s58, v30
	v_add_u32_e32 v58, s59, v23
	v_add_u32_e32 v60, s58, v32
	v_add_u32_e32 v62, s59, v29
	v_add_u32_e32 v64, s58, v34
	v_add_u32_e32 v66, s59, v31
	v_add_u32_e32 v68, s58, v36
	v_add_u32_e32 v70, s59, v33
	v_add_u32_e32 v72, s58, v38
	v_add_u32_e32 v74, s59, v35
	v_add_u32_e32 v76, s58, v40
	v_add_u32_e32 v78, s59, v37
	v_ashrrev_i32_e32 v49, 31, v48
	v_ashrrev_i32_e32 v51, 31, v50
	v_ashrrev_i32_e32 v53, 31, v52
	v_ashrrev_i32_e32 v55, 31, v54
	v_ashrrev_i32_e32 v57, 31, v56
	v_ashrrev_i32_e32 v59, 31, v58
	v_ashrrev_i32_e32 v61, 31, v60
	v_ashrrev_i32_e32 v63, 31, v62
	v_ashrrev_i32_e32 v65, 31, v64
	v_ashrrev_i32_e32 v67, 31, v66
	v_ashrrev_i32_e32 v69, 31, v68
	v_ashrrev_i32_e32 v71, 31, v70
	v_ashrrev_i32_e32 v73, 31, v72
	v_ashrrev_i32_e32 v75, 31, v74
	v_ashrrev_i32_e32 v77, 31, v76
	v_ashrrev_i32_e32 v79, 31, v78
	v_lshlrev_b64 v[48:49], 13, v[48:49]
	v_lshlrev_b64 v[50:51], 13, v[50:51]
	v_lshlrev_b64 v[52:53], 13, v[52:53]
	v_lshlrev_b64 v[54:55], 13, v[54:55]
	v_lshlrev_b64 v[56:57], 13, v[56:57]
	v_lshlrev_b64 v[58:59], 13, v[58:59]
	v_lshlrev_b64 v[60:61], 13, v[60:61]
	v_lshlrev_b64 v[62:63], 13, v[62:63]
	v_lshlrev_b64 v[64:65], 13, v[64:65]
	v_lshlrev_b64 v[66:67], 13, v[66:67]
	v_lshlrev_b64 v[68:69], 13, v[68:69]
	v_lshlrev_b64 v[70:71], 13, v[70:71]
	v_lshlrev_b64 v[72:73], 13, v[72:73]
	v_lshlrev_b64 v[74:75], 13, v[74:75]
	v_lshlrev_b64 v[76:77], 13, v[76:77]
	v_lshlrev_b64 v[78:79], 13, v[78:79]
	v_lshl_add_u64 v[48:49], v[26:27], 0, v[48:49]
	v_lshl_add_u64 v[50:51], v[26:27], 0, v[50:51]
	v_lshl_add_u64 v[52:53], v[26:27], 0, v[52:53]
	v_lshl_add_u64 v[54:55], v[26:27], 0, v[54:55]
	v_lshl_add_u64 v[56:57], v[26:27], 0, v[56:57]
	v_lshl_add_u64 v[58:59], v[26:27], 0, v[58:59]
	v_lshl_add_u64 v[60:61], v[26:27], 0, v[60:61]
	v_lshl_add_u64 v[62:63], v[26:27], 0, v[62:63]
	v_lshl_add_u64 v[64:65], v[26:27], 0, v[64:65]
	v_lshl_add_u64 v[66:67], v[26:27], 0, v[66:67]
	v_lshl_add_u64 v[68:69], v[26:27], 0, v[68:69]
	v_lshl_add_u64 v[70:71], v[26:27], 0, v[70:71]
	v_lshl_add_u64 v[72:73], v[26:27], 0, v[72:73]
	v_lshl_add_u64 v[74:75], v[26:27], 0, v[74:75]
	v_lshl_add_u64 v[76:77], v[26:27], 0, v[76:77]
	v_lshl_add_u64 v[78:79], v[26:27], 0, v[78:79]
	global_load_dword v47, v[48:49], off nt
	global_load_dword v80, v[50:51], off nt
	global_load_dword v81, v[52:53], off nt
	global_load_dword v82, v[54:55], off nt
	global_load_dword v83, v[56:57], off nt
	global_load_dword v84, v[58:59], off nt
	global_load_dword v85, v[60:61], off nt
	global_load_dword v86, v[62:63], off nt
	global_load_dword v87, v[64:65], off nt
	global_load_dword v88, v[66:67], off nt
	global_load_dword v89, v[68:69], off nt
	global_load_dword v90, v[70:71], off nt
	global_load_dword v91, v[72:73], off nt
	global_load_dword v92, v[74:75], off nt
	global_load_dword v93, v[76:77], off nt
	global_load_dword v94, v[78:79], off nt
	s_add_i32 s56, s56, 16
	s_add_i32 s17, s17, 16
	s_add_i32 s57, s57, -16
	v_add_u32_e32 v48, s58, v0
	v_add_u32_e32 v50, s59, v1
	v_add_u32_e32 v52, s58, v8
	v_add_u32_e32 v54, s59, v5
	v_add_u32_e32 v56, s58, v10
	v_add_u32_e32 v58, s59, v7
	v_add_u32_e32 v60, s58, v12
	v_add_u32_e32 v62, s59, v9
	v_add_u32_e32 v64, s58, v14
	v_add_u32_e32 v66, s59, v11
	v_add_u32_e32 v68, s58, v16
	v_add_u32_e32 v70, s59, v13
	v_add_u32_e32 v72, s58, v18
	v_add_u32_e32 v74, s59, v15
	v_add_u32_e32 v76, s58, v20
	v_add_u32_e32 v78, s59, v17
	s_cmp_lg_u32 s57, 0
	v_mad_u64_u32 v[48:49], s[58:59], v48, s35, v[4:5]
	v_mad_u64_u32 v[50:51], s[58:59], v50, s35, v[4:5]
	v_mad_u64_u32 v[52:53], s[58:59], v52, s35, v[4:5]
	v_mad_u64_u32 v[54:55], s[58:59], v54, s35, v[4:5]
	v_mad_u64_u32 v[56:57], s[58:59], v56, s35, v[4:5]
	v_mad_u64_u32 v[58:59], s[58:59], v58, s35, v[4:5]
	v_mad_u64_u32 v[60:61], s[58:59], v60, s35, v[4:5]
	v_mad_u64_u32 v[62:63], s[58:59], v62, s35, v[4:5]
	v_mad_u64_u32 v[64:65], s[58:59], v64, s35, v[4:5]
	v_mad_u64_u32 v[66:67], s[58:59], v66, s35, v[4:5]
	v_mad_u64_u32 v[68:69], s[58:59], v68, s35, v[4:5]
	v_mad_u64_u32 v[70:71], s[58:59], v70, s35, v[4:5]
	v_mad_u64_u32 v[72:73], s[58:59], v72, s35, v[4:5]
	v_mad_u64_u32 v[74:75], s[58:59], v74, s35, v[4:5]
	v_mad_u64_u32 v[76:77], s[58:59], v76, s35, v[4:5]
	v_mad_u64_u32 v[78:79], s[58:59], v78, s35, v[4:5]
	s_waitcnt vmcnt(15)
	ds_write_b32 v48, v47
	s_waitcnt vmcnt(14)
	ds_write_b32 v50, v80
	s_waitcnt vmcnt(13)
	ds_write_b32 v52, v81
	s_waitcnt vmcnt(12)
	ds_write_b32 v54, v82
	s_waitcnt vmcnt(11)
	ds_write_b32 v56, v83
	s_waitcnt vmcnt(10)
	ds_write_b32 v58, v84
	s_waitcnt vmcnt(9)
	ds_write_b32 v60, v85
	s_waitcnt vmcnt(8)
	ds_write_b32 v62, v86
	s_waitcnt vmcnt(7)
	ds_write_b32 v64, v87
	s_waitcnt vmcnt(6)
	ds_write_b32 v66, v88
	s_waitcnt vmcnt(5)
	ds_write_b32 v68, v89
	s_waitcnt vmcnt(4)
	ds_write_b32 v70, v90
	s_waitcnt vmcnt(3)
	ds_write_b32 v72, v91
	s_waitcnt vmcnt(2)
	ds_write_b32 v74, v92
	s_waitcnt vmcnt(1)
	ds_write_b32 v76, v93
	s_waitcnt vmcnt(0)
	ds_write_b32 v78, v94
	s_cbranch_scc1 .LBB0_58
	s_waitcnt lgkmcnt(0)
	s_lshl_b64 s[8:9], s[8:9], 1
	ds_read2_b32 v[30:31], v42 offset1:8
	s_add_u32 s8, s27, s8
	ds_read2_b32 v[34:35], v42 offset0:33 offset1:41
	s_addc_u32 s9, s28, s9
	s_lshl_b32 s16, s16, 1
	s_add_u32 s8, s8, s16
	ds_read2_b32 v[36:37], v42 offset0:66 offset1:74
	s_addc_u32 s9, s9, 0
	v_lshlrev_b32_e32 v2, 1, v6
	ds_read2_b32 v[48:49], v42 offset0:99 offset1:107
	v_lshl_add_u64 v[32:33], s[8:9], 0, v[2:3]
	s_waitcnt lgkmcnt(3)
	v_bfe_u32 v2, v30, 16, 1
	v_add3_u32 v2, v30, v2, s37
	s_waitcnt lgkmcnt(2)
	v_bfe_u32 v19, v34, 16, 1
	ds_read2_b32 v[50:51], v42 offset0:132 offset1:140
	v_lshrrev_b32_e32 v2, 16, v2
	v_add3_u32 v19, v34, v19, s37
	ds_read2_b32 v[52:53], v42 offset0:165 offset1:173
	v_and_or_b32 v26, v19, s38, v2
	s_waitcnt lgkmcnt(3)
	v_bfe_u32 v2, v36, 16, 1
	v_add3_u32 v2, v36, v2, s37
	s_waitcnt lgkmcnt(2)
	v_bfe_u32 v19, v48, 16, 1
	ds_read2_b32 v[54:55], v42 offset0:198 offset1:206
	v_lshrrev_b32_e32 v2, 16, v2
	v_add3_u32 v19, v48, v19, s37
	ds_read2_b32 v[56:57], v42 offset0:231 offset1:239
	v_and_or_b32 v27, v19, s38, v2
	s_waitcnt lgkmcnt(3)
	v_bfe_u32 v2, v50, 16, 1
	v_add3_u32 v2, v50, v2, s37
	s_waitcnt lgkmcnt(2)
	v_bfe_u32 v19, v52, 16, 1
	v_lshrrev_b32_e32 v2, 16, v2
	v_add3_u32 v19, v52, v19, s37
	v_and_or_b32 v28, v19, s38, v2
	s_waitcnt lgkmcnt(1)
	v_bfe_u32 v2, v54, 16, 1
	v_add3_u32 v2, v54, v2, s37
	s_waitcnt lgkmcnt(0)
	v_bfe_u32 v19, v56, 16, 1
	v_lshrrev_b32_e32 v2, 16, v2
	v_add3_u32 v19, v56, v19, s37
	v_add_u32_e32 v58, s2, v41
	v_and_or_b32 v29, v19, s38, v2
	v_ashrrev_i32_e32 v59, 31, v58
	v_bfe_u32 v2, v31, 16, 1
	v_lshlrev_b64 v[58:59], 12, v[58:59]
	v_add3_u32 v2, v31, v2, s37
	v_bfe_u32 v19, v35, 16, 1
	v_lshl_add_u64 v[58:59], v[32:33], 0, v[58:59]
	v_lshrrev_b32_e32 v2, 16, v2
	v_add3_u32 v19, v35, v19, s37
	global_store_dwordx4 v[58:59], v[26:29], off
	v_add_u32_e32 v30, s2, v43
	v_ashrrev_i32_e32 v31, 31, v30
	v_and_or_b32 v26, v19, s38, v2
	v_bfe_u32 v2, v37, 16, 1
	v_add3_u32 v2, v37, v2, s37
	v_bfe_u32 v19, v49, 16, 1
	v_lshrrev_b32_e32 v2, 16, v2
	v_add3_u32 v19, v49, v19, s37
	v_and_or_b32 v27, v19, s38, v2
	v_bfe_u32 v2, v51, 16, 1
	v_add3_u32 v2, v51, v2, s37
	v_bfe_u32 v19, v53, 16, 1
	v_lshrrev_b32_e32 v2, 16, v2
	v_add3_u32 v19, v53, v19, s37
	v_and_or_b32 v28, v19, s38, v2
	v_bfe_u32 v2, v55, 16, 1
	v_add3_u32 v2, v55, v2, s37
	v_bfe_u32 v19, v57, 16, 1
	v_lshrrev_b32_e32 v2, 16, v2
	v_add3_u32 v19, v57, v19, s37
	v_lshlrev_b64 v[30:31], 12, v[30:31]
	v_and_or_b32 v29, v19, s38, v2
	ds_read2_b32 v[34:35], v42 offset0:16 offset1:24
	v_lshl_add_u64 v[30:31], v[32:33], 0, v[30:31]
	global_store_dwordx4 v[30:31], v[26:29], off
	ds_read2_b32 v[30:31], v42 offset0:49 offset1:57
	ds_read2_b32 v[36:37], v42 offset0:82 offset1:90
	ds_read2_b32 v[48:49], v42 offset0:115 offset1:123
	s_waitcnt lgkmcnt(3)
	v_bfe_u32 v2, v34, 16, 1
	v_add3_u32 v2, v34, v2, s37
	s_waitcnt lgkmcnt(2)
	v_bfe_u32 v19, v30, 16, 1
	ds_read2_b32 v[50:51], v42 offset0:148 offset1:156
	v_lshrrev_b32_e32 v2, 16, v2
	v_add3_u32 v19, v30, v19, s37
	ds_read2_b32 v[52:53], v42 offset0:181 offset1:189
	v_and_or_b32 v26, v19, s38, v2
	s_waitcnt lgkmcnt(3)
	v_bfe_u32 v2, v36, 16, 1
	v_add3_u32 v2, v36, v2, s37
	s_waitcnt lgkmcnt(2)
	v_bfe_u32 v19, v48, 16, 1
	ds_read2_b32 v[54:55], v42 offset0:214 offset1:222
	v_lshrrev_b32_e32 v2, 16, v2
	v_add3_u32 v19, v48, v19, s37
	ds_read2_b32 v[56:57], v42 offset0:247 offset1:255
	v_and_or_b32 v27, v19, s38, v2
	s_waitcnt lgkmcnt(3)
	v_bfe_u32 v2, v50, 16, 1
	v_add3_u32 v2, v50, v2, s37
	s_waitcnt lgkmcnt(2)
	v_bfe_u32 v19, v52, 16, 1
	v_lshrrev_b32_e32 v2, 16, v2
	v_add3_u32 v19, v52, v19, s37
	v_and_or_b32 v28, v19, s38, v2
	s_waitcnt lgkmcnt(1)
	v_bfe_u32 v2, v54, 16, 1
	v_add3_u32 v2, v54, v2, s37
	s_waitcnt lgkmcnt(0)
	v_bfe_u32 v19, v56, 16, 1
	v_lshrrev_b32_e32 v2, 16, v2
	v_add3_u32 v19, v56, v19, s37
	v_add_u32_e32 v58, s2, v44
	v_and_or_b32 v29, v19, s38, v2
	v_ashrrev_i32_e32 v59, 31, v58
	v_bfe_u32 v19, v35, 16, 1
	v_lshlrev_b64 v[58:59], 12, v[58:59]
	v_bfe_u32 v2, v31, 16, 1
	v_add3_u32 v19, v35, v19, s37
	v_lshl_add_u64 v[58:59], v[32:33], 0, v[58:59]
	v_add3_u32 v2, v31, v2, s37
	v_lshrrev_b32_e32 v19, 16, v19
	global_store_dwordx4 v[58:59], v[26:29], off
	v_add_u32_e32 v30, s2, v45
	v_ashrrev_i32_e32 v31, 31, v30
	v_and_or_b32 v26, v2, s38, v19
	v_bfe_u32 v19, v37, 16, 1
	v_bfe_u32 v2, v49, 16, 1
	v_add3_u32 v19, v37, v19, s37
	v_add3_u32 v2, v49, v2, s37
	v_lshrrev_b32_e32 v19, 16, v19
	v_and_or_b32 v27, v2, s38, v19
	v_bfe_u32 v19, v51, 16, 1
	v_bfe_u32 v2, v53, 16, 1
	v_add3_u32 v19, v51, v19, s37
	v_add3_u32 v2, v53, v2, s37
	v_lshrrev_b32_e32 v19, 16, v19
	v_and_or_b32 v28, v2, s38, v19
	v_bfe_u32 v19, v55, 16, 1
	v_bfe_u32 v2, v57, 16, 1
	v_add3_u32 v19, v55, v19, s37
	v_add3_u32 v2, v57, v2, s37
	v_lshrrev_b32_e32 v19, 16, v19
	v_lshlrev_b64 v[30:31], 12, v[30:31]
	v_and_or_b32 v29, v2, s38, v19
	v_lshl_add_u64 v[30:31], v[32:33], 0, v[30:31]
	global_store_dwordx4 v[30:31], v[26:29], off
	s_waitcnt lgkmcnt(0)
	s_mov_b64 s[8:9], 0

.LBB0_62:
	s_lshl_b32 s56, s9, 1
	s_lshl_b32 s57, s2, 1
	v_add_u32_e32 v48, s56, v2
	v_add_u32_e32 v50, s57, v19
	v_add_u32_e32 v52, s56, v26
	v_add_u32_e32 v54, s57, v21
	v_add_u32_e32 v56, s56, v28
	v_add_u32_e32 v58, s57, v23
	v_add_u32_e32 v60, s56, v30
	v_add_u32_e32 v62, s57, v27
	v_add_u32_e32 v64, s56, v32
	v_add_u32_e32 v66, s57, v29
	v_add_u32_e32 v68, s56, v34
	v_add_u32_e32 v70, s57, v31
	v_add_u32_e32 v72, s56, v36
	v_add_u32_e32 v74, s57, v33
	v_add_u32_e32 v76, s56, v38
	v_add_u32_e32 v78, s57, v35
	v_ashrrev_i32_e32 v49, 31, v48
	v_ashrrev_i32_e32 v51, 31, v50
	v_ashrrev_i32_e32 v53, 31, v52
	v_ashrrev_i32_e32 v55, 31, v54
	v_ashrrev_i32_e32 v57, 31, v56
	v_ashrrev_i32_e32 v59, 31, v58
	v_ashrrev_i32_e32 v61, 31, v60
	v_ashrrev_i32_e32 v63, 31, v62
	v_ashrrev_i32_e32 v65, 31, v64
	v_ashrrev_i32_e32 v67, 31, v66
	v_ashrrev_i32_e32 v69, 31, v68
	v_ashrrev_i32_e32 v71, 31, v70
	v_ashrrev_i32_e32 v73, 31, v72
	v_ashrrev_i32_e32 v75, 31, v74
	v_ashrrev_i32_e32 v77, 31, v76
	v_ashrrev_i32_e32 v79, 31, v78
	v_lshlrev_b64 v[48:49], 13, v[48:49]
	v_lshlrev_b64 v[50:51], 13, v[50:51]
	v_lshlrev_b64 v[52:53], 13, v[52:53]
	v_lshlrev_b64 v[54:55], 13, v[54:55]
	v_lshlrev_b64 v[56:57], 13, v[56:57]
	v_lshlrev_b64 v[58:59], 13, v[58:59]
	v_lshlrev_b64 v[60:61], 13, v[60:61]
	v_lshlrev_b64 v[62:63], 13, v[62:63]
	v_lshlrev_b64 v[64:65], 13, v[64:65]
	v_lshlrev_b64 v[66:67], 13, v[66:67]
	v_lshlrev_b64 v[68:69], 13, v[68:69]
	v_lshlrev_b64 v[70:71], 13, v[70:71]
	v_lshlrev_b64 v[72:73], 13, v[72:73]
	v_lshlrev_b64 v[74:75], 13, v[74:75]
	v_lshlrev_b64 v[76:77], 13, v[76:77]
	v_lshlrev_b64 v[78:79], 13, v[78:79]
	v_lshl_add_u64 v[48:49], v[24:25], 0, v[48:49]
	v_lshl_add_u64 v[50:51], v[24:25], 0, v[50:51]
	v_lshl_add_u64 v[52:53], v[24:25], 0, v[52:53]
	v_lshl_add_u64 v[54:55], v[24:25], 0, v[54:55]
	v_lshl_add_u64 v[56:57], v[24:25], 0, v[56:57]
	v_lshl_add_u64 v[58:59], v[24:25], 0, v[58:59]
	v_lshl_add_u64 v[60:61], v[24:25], 0, v[60:61]
	v_lshl_add_u64 v[62:63], v[24:25], 0, v[62:63]
	v_lshl_add_u64 v[64:65], v[24:25], 0, v[64:65]
	v_lshl_add_u64 v[66:67], v[24:25], 0, v[66:67]
	v_lshl_add_u64 v[68:69], v[24:25], 0, v[68:69]
	v_lshl_add_u64 v[70:71], v[24:25], 0, v[70:71]
	v_lshl_add_u64 v[72:73], v[24:25], 0, v[72:73]
	v_lshl_add_u64 v[74:75], v[24:25], 0, v[74:75]
	v_lshl_add_u64 v[76:77], v[24:25], 0, v[76:77]
	v_lshl_add_u64 v[78:79], v[24:25], 0, v[78:79]
	global_load_dword v37, v[48:49], off nt
	global_load_dword v40, v[50:51], off nt
	global_load_dword v47, v[52:53], off nt
	global_load_dword v80, v[54:55], off nt
	global_load_dword v81, v[56:57], off nt
	global_load_dword v82, v[58:59], off nt
	global_load_dword v83, v[60:61], off nt
	global_load_dword v84, v[62:63], off nt
	global_load_dword v85, v[64:65], off nt
	global_load_dword v86, v[66:67], off nt
	global_load_dword v87, v[68:69], off nt
	global_load_dword v88, v[70:71], off nt
	global_load_dword v89, v[72:73], off nt
	global_load_dword v90, v[74:75], off nt
	global_load_dword v91, v[76:77], off nt
	global_load_dword v92, v[78:79], off nt
	s_add_i32 s9, s9, 16
	s_add_i32 s2, s2, 16
	s_add_i32 s17, s17, -16
	v_add_u32_e32 v48, s56, v0
	v_add_u32_e32 v50, s57, v1
	v_add_u32_e32 v52, s56, v8
	v_add_u32_e32 v54, s57, v5
	v_add_u32_e32 v56, s56, v10
	v_add_u32_e32 v58, s57, v7
	v_add_u32_e32 v60, s56, v12
	v_add_u32_e32 v62, s57, v9
	v_add_u32_e32 v64, s56, v14
	v_add_u32_e32 v66, s57, v11
	v_add_u32_e32 v68, s56, v16
	v_add_u32_e32 v70, s57, v13
	v_add_u32_e32 v72, s56, v18
	v_add_u32_e32 v74, s57, v15
	v_add_u32_e32 v76, s56, v20
	v_add_u32_e32 v78, s57, v17
	s_cmp_lg_u32 s17, 0
	v_mad_u64_u32 v[48:49], s[56:57], v48, s35, v[4:5]
	v_mad_u64_u32 v[50:51], s[56:57], v50, s35, v[4:5]
	v_mad_u64_u32 v[52:53], s[56:57], v52, s35, v[4:5]
	v_mad_u64_u32 v[54:55], s[56:57], v54, s35, v[4:5]
	v_mad_u64_u32 v[56:57], s[56:57], v56, s35, v[4:5]
	v_mad_u64_u32 v[58:59], s[56:57], v58, s35, v[4:5]
	v_mad_u64_u32 v[60:61], s[56:57], v60, s35, v[4:5]
	v_mad_u64_u32 v[62:63], s[56:57], v62, s35, v[4:5]
	v_mad_u64_u32 v[64:65], s[56:57], v64, s35, v[4:5]
	v_mad_u64_u32 v[66:67], s[56:57], v66, s35, v[4:5]
	v_mad_u64_u32 v[68:69], s[56:57], v68, s35, v[4:5]
	v_mad_u64_u32 v[70:71], s[56:57], v70, s35, v[4:5]
	v_mad_u64_u32 v[72:73], s[56:57], v72, s35, v[4:5]
	v_mad_u64_u32 v[74:75], s[56:57], v74, s35, v[4:5]
	v_mad_u64_u32 v[76:77], s[56:57], v76, s35, v[4:5]
	v_mad_u64_u32 v[78:79], s[56:57], v78, s35, v[4:5]
	s_waitcnt vmcnt(15)
	ds_write_b32 v48, v37
	s_waitcnt vmcnt(14)
	ds_write_b32 v50, v40
	s_waitcnt vmcnt(13)
	ds_write_b32 v52, v47
	s_waitcnt vmcnt(12)
	ds_write_b32 v54, v80
	s_waitcnt vmcnt(11)
	ds_write_b32 v56, v81
	s_waitcnt vmcnt(10)
	ds_write_b32 v58, v82
	s_waitcnt vmcnt(9)
	ds_write_b32 v60, v83
	s_waitcnt vmcnt(8)
	ds_write_b32 v62, v84
	s_waitcnt vmcnt(7)
	ds_write_b32 v64, v85
	s_waitcnt vmcnt(6)
	ds_write_b32 v66, v86
	s_waitcnt vmcnt(5)
	ds_write_b32 v68, v87
	s_waitcnt vmcnt(4)
	ds_write_b32 v70, v88
	s_waitcnt vmcnt(3)
	ds_write_b32 v72, v89
	s_waitcnt vmcnt(2)
	ds_write_b32 v74, v90
	s_waitcnt vmcnt(1)
	ds_write_b32 v76, v91
	s_waitcnt vmcnt(0)
	ds_write_b32 v78, v92
	s_cbranch_scc1 .LBB0_62
	s_waitcnt lgkmcnt(0)
	s_lshl_b64 s[56:57], s[6:7], 21
	s_add_u32 s2, s29, s56
	ds_read2_b32 v[28:29], v42 offset1:8
	s_addc_u32 s7, s30, s57
	s_ashr_i32 s17, s16, 31
	ds_read2_b32 v[32:33], v42 offset0:33 offset1:41
	s_lshl_b64 s[16:17], s[16:17], 1
	s_add_u32 s16, s2, s16
	ds_read2_b32 v[34:35], v42 offset0:66 offset1:74
	s_addc_u32 s17, s7, s17
	v_lshlrev_b32_e32 v2, 1, v6
	ds_read2_b32 v[36:37], v42 offset0:99 offset1:107
	v_lshl_add_u64 v[30:31], s[16:17], 0, v[2:3]
	s_waitcnt lgkmcnt(3)
	v_bfe_u32 v2, v28, 16, 1
	v_add3_u32 v2, v28, v2, s37
	s_waitcnt lgkmcnt(2)
	v_bfe_u32 v19, v32, 16, 1
	ds_read2_b32 v[48:49], v42 offset0:132 offset1:140
	v_lshrrev_b32_e32 v2, 16, v2
	v_add3_u32 v19, v32, v19, s37
	ds_read2_b32 v[50:51], v42 offset0:165 offset1:173
	v_and_or_b32 v24, v19, s38, v2
	s_waitcnt lgkmcnt(3)
	v_bfe_u32 v2, v34, 16, 1
	v_add3_u32 v2, v34, v2, s37
	s_waitcnt lgkmcnt(2)
	v_bfe_u32 v19, v36, 16, 1
	ds_read2_b32 v[52:53], v42 offset0:198 offset1:206
	v_lshrrev_b32_e32 v2, 16, v2
	v_add3_u32 v19, v36, v19, s37
	ds_read2_b32 v[54:55], v42 offset0:231 offset1:239
	v_and_or_b32 v25, v19, s38, v2
	s_waitcnt lgkmcnt(3)
	v_bfe_u32 v2, v48, 16, 1
	v_add3_u32 v2, v48, v2, s37
	s_waitcnt lgkmcnt(2)
	v_bfe_u32 v19, v50, 16, 1
	v_lshrrev_b32_e32 v2, 16, v2
	v_add3_u32 v19, v50, v19, s37
	v_and_or_b32 v26, v19, s38, v2
	s_waitcnt lgkmcnt(1)
	v_bfe_u32 v2, v52, 16, 1
	v_add3_u32 v2, v52, v2, s37
	s_waitcnt lgkmcnt(0)
	v_bfe_u32 v19, v54, 16, 1
	v_lshrrev_b32_e32 v2, 16, v2
	v_add3_u32 v19, v54, v19, s37
	v_add_u32_e32 v56, s8, v41
	v_and_or_b32 v27, v19, s38, v2
	v_ashrrev_i32_e32 v57, 31, v56
	v_bfe_u32 v2, v29, 16, 1
	v_lshlrev_b64 v[56:57], 10, v[56:57]
	v_add3_u32 v2, v29, v2, s37
	v_bfe_u32 v19, v33, 16, 1
	v_lshl_add_u64 v[56:57], v[30:31], 0, v[56:57]
	v_lshrrev_b32_e32 v2, 16, v2
	v_add3_u32 v19, v33, v19, s37
	global_store_dwordx4 v[56:57], v[24:27], off
	v_add_u32_e32 v28, s8, v43
	v_ashrrev_i32_e32 v29, 31, v28
	v_and_or_b32 v24, v19, s38, v2
	v_bfe_u32 v2, v35, 16, 1
	v_add3_u32 v2, v35, v2, s37
	v_bfe_u32 v19, v37, 16, 1
	v_lshrrev_b32_e32 v2, 16, v2
	v_add3_u32 v19, v37, v19, s37
	v_and_or_b32 v25, v19, s38, v2
	v_bfe_u32 v2, v49, 16, 1
	v_add3_u32 v2, v49, v2, s37
	v_bfe_u32 v19, v51, 16, 1
	v_lshrrev_b32_e32 v2, 16, v2
	v_add3_u32 v19, v51, v19, s37
	v_and_or_b32 v26, v19, s38, v2
	v_bfe_u32 v2, v53, 16, 1
	v_add3_u32 v2, v53, v2, s37
	v_bfe_u32 v19, v55, 16, 1
	v_lshrrev_b32_e32 v2, 16, v2
	v_add3_u32 v19, v55, v19, s37
	v_lshlrev_b64 v[28:29], 10, v[28:29]
	v_and_or_b32 v27, v19, s38, v2
	ds_read2_b32 v[32:33], v42 offset0:16 offset1:24
	v_lshl_add_u64 v[28:29], v[30:31], 0, v[28:29]
	global_store_dwordx4 v[28:29], v[24:27], off
	ds_read2_b32 v[28:29], v42 offset0:49 offset1:57
	ds_read2_b32 v[34:35], v42 offset0:82 offset1:90
	ds_read2_b32 v[36:37], v42 offset0:115 offset1:123
	s_waitcnt lgkmcnt(3)
	v_bfe_u32 v2, v32, 16, 1
	v_add3_u32 v2, v32, v2, s37
	s_waitcnt lgkmcnt(2)
	v_bfe_u32 v19, v28, 16, 1
	ds_read2_b32 v[48:49], v42 offset0:148 offset1:156
	v_lshrrev_b32_e32 v2, 16, v2
	v_add3_u32 v19, v28, v19, s37
	ds_read2_b32 v[50:51], v42 offset0:181 offset1:189
	v_and_or_b32 v24, v19, s38, v2
	s_waitcnt lgkmcnt(3)
	v_bfe_u32 v2, v34, 16, 1
	v_add3_u32 v2, v34, v2, s37
	s_waitcnt lgkmcnt(2)
	v_bfe_u32 v19, v36, 16, 1
	ds_read2_b32 v[52:53], v42 offset0:214 offset1:222
	v_lshrrev_b32_e32 v2, 16, v2
	v_add3_u32 v19, v36, v19, s37
	ds_read2_b32 v[54:55], v42 offset0:247 offset1:255
	v_and_or_b32 v25, v19, s38, v2
	s_waitcnt lgkmcnt(3)
	v_bfe_u32 v2, v48, 16, 1
	v_add3_u32 v2, v48, v2, s37
	s_waitcnt lgkmcnt(2)
	v_bfe_u32 v19, v50, 16, 1
	v_lshrrev_b32_e32 v2, 16, v2
	v_add3_u32 v19, v50, v19, s37
	v_and_or_b32 v26, v19, s38, v2
	s_waitcnt lgkmcnt(1)
	v_bfe_u32 v2, v52, 16, 1
	v_add3_u32 v2, v52, v2, s37
	s_waitcnt lgkmcnt(0)
	v_bfe_u32 v19, v54, 16, 1
	v_lshrrev_b32_e32 v2, 16, v2
	v_add3_u32 v19, v54, v19, s37
	v_add_u32_e32 v56, s8, v44
	v_and_or_b32 v27, v19, s38, v2
	v_ashrrev_i32_e32 v57, 31, v56
	v_bfe_u32 v19, v33, 16, 1
	v_lshlrev_b64 v[56:57], 10, v[56:57]
	v_bfe_u32 v2, v29, 16, 1
	v_add3_u32 v19, v33, v19, s37
	v_lshl_add_u64 v[56:57], v[30:31], 0, v[56:57]
	v_add3_u32 v2, v29, v2, s37
	v_lshrrev_b32_e32 v19, 16, v19
	global_store_dwordx4 v[56:57], v[24:27], off
	v_add_u32_e32 v28, s8, v45
	v_ashrrev_i32_e32 v29, 31, v28
	v_and_or_b32 v24, v2, s38, v19
	v_bfe_u32 v19, v35, 16, 1
	v_bfe_u32 v2, v37, 16, 1
	v_add3_u32 v19, v35, v19, s37
	v_add3_u32 v2, v37, v2, s37
	v_lshrrev_b32_e32 v19, 16, v19
	v_and_or_b32 v25, v2, s38, v19
	v_bfe_u32 v19, v49, 16, 1
	v_bfe_u32 v2, v51, 16, 1
	v_add3_u32 v19, v49, v19, s37
	v_add3_u32 v2, v51, v2, s37
	v_lshrrev_b32_e32 v19, 16, v19
	v_and_or_b32 v26, v2, s38, v19
	v_bfe_u32 v19, v53, 16, 1
	v_bfe_u32 v2, v55, 16, 1
	v_add3_u32 v19, v53, v19, s37
	v_add3_u32 v2, v55, v2, s37
	v_lshrrev_b32_e32 v19, 16, v19
	v_lshlrev_b64 v[28:29], 10, v[28:29]
	v_and_or_b32 v27, v2, s38, v19
	v_lshl_add_u64 v[28:29], v[30:31], 0, v[28:29]
	global_store_dwordx4 v[28:29], v[24:27], off
	s_waitcnt lgkmcnt(0)

.LBB0_67:
	s_lshl_b32 s17, s7, 1
	s_lshl_b32 s55, s2, 1
	v_add_u32_e32 v37, s17, v2
	v_add_u32_e32 v40, s55, v19
	v_add_u32_e32 v47, s17, v26
	v_add_u32_e32 v54, s55, v21
	v_add_u32_e32 v56, s17, v28
	v_add_u32_e32 v58, s55, v23
	v_add_u32_e32 v60, s17, v30
	v_add_u32_e32 v62, s55, v27
	v_add_u32_e32 v64, s17, v32
	v_add_u32_e32 v66, s55, v29
	v_add_u32_e32 v68, s17, v34
	v_add_u32_e32 v70, s55, v31
	v_add_u32_e32 v72, s17, v36
	v_add_u32_e32 v74, s55, v33
	v_add_u32_e32 v76, s17, v38
	v_add_u32_e32 v78, s55, v35
	v_mad_i64_i32 v[48:49], s[56:57], v37, s53, v[24:25]
	v_mad_i64_i32 v[50:51], s[56:57], v40, s53, v[24:25]
	v_mad_i64_i32 v[52:53], s[56:57], v47, s53, v[24:25]
	v_mad_i64_i32 v[54:55], s[56:57], v54, s53, v[24:25]
	v_mad_i64_i32 v[56:57], s[56:57], v56, s53, v[24:25]
	v_mad_i64_i32 v[58:59], s[56:57], v58, s53, v[24:25]
	v_mad_i64_i32 v[60:61], s[56:57], v60, s53, v[24:25]
	v_mad_i64_i32 v[62:63], s[56:57], v62, s53, v[24:25]
	v_mad_i64_i32 v[64:65], s[56:57], v64, s53, v[24:25]
	v_mad_i64_i32 v[66:67], s[56:57], v66, s53, v[24:25]
	v_mad_i64_i32 v[68:69], s[56:57], v68, s53, v[24:25]
	v_mad_i64_i32 v[70:71], s[56:57], v70, s53, v[24:25]
	v_mad_i64_i32 v[72:73], s[56:57], v72, s53, v[24:25]
	v_mad_i64_i32 v[74:75], s[56:57], v74, s53, v[24:25]
	v_mad_i64_i32 v[76:77], s[56:57], v76, s53, v[24:25]
	v_mad_i64_i32 v[78:79], s[56:57], v78, s53, v[24:25]
	global_load_dword v37, v[48:49], off nt
	global_load_dword v40, v[50:51], off nt
	global_load_dword v47, v[52:53], off nt
	global_load_dword v80, v[54:55], off nt
	global_load_dword v81, v[56:57], off nt
	global_load_dword v82, v[58:59], off nt
	global_load_dword v83, v[60:61], off nt
	global_load_dword v84, v[62:63], off nt
	global_load_dword v85, v[64:65], off nt
	global_load_dword v86, v[66:67], off nt
	global_load_dword v87, v[68:69], off nt
	global_load_dword v88, v[70:71], off nt
	global_load_dword v89, v[72:73], off nt
	global_load_dword v90, v[74:75], off nt
	global_load_dword v91, v[76:77], off nt
	global_load_dword v92, v[78:79], off nt
	s_add_i32 s7, s7, 16
	s_add_i32 s2, s2, 16
	s_add_i32 s9, s9, -16
	v_add_u32_e32 v48, s17, v0
	v_add_u32_e32 v50, s55, v1
	v_add_u32_e32 v52, s17, v8
	v_add_u32_e32 v54, s55, v5
	v_add_u32_e32 v56, s17, v10
	v_add_u32_e32 v58, s55, v7
	v_add_u32_e32 v60, s17, v12
	v_add_u32_e32 v62, s55, v9
	v_add_u32_e32 v64, s17, v14
	v_add_u32_e32 v66, s55, v11
	v_add_u32_e32 v68, s17, v16
	v_add_u32_e32 v70, s55, v13
	v_add_u32_e32 v72, s17, v18
	v_add_u32_e32 v74, s55, v15
	v_add_u32_e32 v76, s17, v20
	v_add_u32_e32 v78, s55, v17
	s_cmp_lg_u32 s9, 0
	v_mad_u64_u32 v[48:49], s[56:57], v48, s35, v[4:5]
	v_mad_u64_u32 v[50:51], s[56:57], v50, s35, v[4:5]
	v_mad_u64_u32 v[52:53], s[56:57], v52, s35, v[4:5]
	v_mad_u64_u32 v[54:55], s[56:57], v54, s35, v[4:5]
	v_mad_u64_u32 v[56:57], s[56:57], v56, s35, v[4:5]
	v_mad_u64_u32 v[58:59], s[56:57], v58, s35, v[4:5]
	v_mad_u64_u32 v[60:61], s[56:57], v60, s35, v[4:5]
	v_mad_u64_u32 v[62:63], s[56:57], v62, s35, v[4:5]
	v_mad_u64_u32 v[64:65], s[56:57], v64, s35, v[4:5]
	v_mad_u64_u32 v[66:67], s[56:57], v66, s35, v[4:5]
	v_mad_u64_u32 v[68:69], s[56:57], v68, s35, v[4:5]
	v_mad_u64_u32 v[70:71], s[56:57], v70, s35, v[4:5]
	v_mad_u64_u32 v[72:73], s[56:57], v72, s35, v[4:5]
	v_mad_u64_u32 v[74:75], s[56:57], v74, s35, v[4:5]
	v_mad_u64_u32 v[76:77], s[56:57], v76, s35, v[4:5]
	v_mad_u64_u32 v[78:79], s[56:57], v78, s35, v[4:5]
	s_waitcnt vmcnt(15)
	ds_write_b32 v48, v37
	s_waitcnt vmcnt(14)
	ds_write_b32 v50, v40
	s_waitcnt vmcnt(13)
	ds_write_b32 v52, v47
	s_waitcnt vmcnt(12)
	ds_write_b32 v54, v80
	s_waitcnt vmcnt(11)
	ds_write_b32 v56, v81
	s_waitcnt vmcnt(10)
	ds_write_b32 v58, v82
	s_waitcnt vmcnt(9)
	ds_write_b32 v60, v83
	s_waitcnt vmcnt(8)
	ds_write_b32 v62, v84
	s_waitcnt vmcnt(7)
	ds_write_b32 v64, v85
	s_waitcnt vmcnt(6)
	ds_write_b32 v66, v86
	s_waitcnt vmcnt(5)
	ds_write_b32 v68, v87
	s_waitcnt vmcnt(4)
	ds_write_b32 v70, v88
	s_waitcnt vmcnt(3)
	ds_write_b32 v72, v89
	s_waitcnt vmcnt(2)
	ds_write_b32 v74, v90
	s_waitcnt vmcnt(1)
	ds_write_b32 v76, v91
	s_waitcnt vmcnt(0)
	ds_write_b32 v78, v92
	s_cbranch_scc1 .LBB0_67
	s_waitcnt lgkmcnt(0)
	s_mul_hi_i32 s2, s6, 0xf00000
	s_mul_i32 s6, s6, 0xf00000
	s_add_u32 s9, s31, s6
	ds_read2_b32 v[28:29], v42 offset1:8
	s_addc_u32 s2, s34, s2
	s_ashr_i32 s17, s16, 31
	ds_read2_b32 v[32:33], v42 offset0:33 offset1:41
	s_lshl_b64 s[6:7], s[16:17], 1
	s_add_u32 s6, s9, s6
	ds_read2_b32 v[34:35], v42 offset0:66 offset1:74
	s_addc_u32 s7, s2, s7
	v_lshlrev_b32_e32 v2, 1, v6
	ds_read2_b32 v[36:37], v42 offset0:99 offset1:107
	v_lshl_add_u64 v[30:31], s[6:7], 0, v[2:3]
	s_waitcnt lgkmcnt(3)
	v_bfe_u32 v2, v28, 16, 1
	v_add3_u32 v2, v28, v2, s37
	s_waitcnt lgkmcnt(2)
	v_bfe_u32 v19, v32, 16, 1
	ds_read2_b32 v[48:49], v42 offset0:132 offset1:140
	v_lshrrev_b32_e32 v2, 16, v2
	v_add3_u32 v19, v32, v19, s37
	ds_read2_b32 v[50:51], v42 offset0:165 offset1:173
	v_and_or_b32 v24, v19, s38, v2
	s_waitcnt lgkmcnt(3)
	v_bfe_u32 v2, v34, 16, 1
	v_add3_u32 v2, v34, v2, s37
	s_waitcnt lgkmcnt(2)
	v_bfe_u32 v19, v36, 16, 1
	ds_read2_b32 v[52:53], v42 offset0:198 offset1:206
	v_lshrrev_b32_e32 v2, 16, v2
	v_add3_u32 v19, v36, v19, s37
	ds_read2_b32 v[54:55], v42 offset0:231 offset1:239
	v_and_or_b32 v25, v19, s38, v2
	s_waitcnt lgkmcnt(3)
	v_bfe_u32 v2, v48, 16, 1
	v_add3_u32 v2, v48, v2, s37
	s_waitcnt lgkmcnt(2)
	v_bfe_u32 v19, v50, 16, 1
	v_lshrrev_b32_e32 v2, 16, v2
	v_add3_u32 v19, v50, v19, s37
	v_and_or_b32 v26, v19, s38, v2
	s_waitcnt lgkmcnt(1)
	v_bfe_u32 v2, v52, 16, 1
	v_add3_u32 v2, v52, v2, s37
	s_waitcnt lgkmcnt(0)
	v_bfe_u32 v19, v54, 16, 1
	v_lshrrev_b32_e32 v2, 16, v2
	v_add3_u32 v19, v54, v19, s37
	v_add_u32_e32 v56, s8, v41
	v_and_or_b32 v27, v19, s38, v2
	v_ashrrev_i32_e32 v57, 31, v56
	v_bfe_u32 v2, v29, 16, 1
	v_lshlrev_b64 v[56:57], 12, v[56:57]
	v_add3_u32 v2, v29, v2, s37
	v_bfe_u32 v19, v33, 16, 1
	v_lshl_add_u64 v[56:57], v[30:31], 0, v[56:57]
	v_lshrrev_b32_e32 v2, 16, v2
	v_add3_u32 v19, v33, v19, s37
	global_store_dwordx4 v[56:57], v[24:27], off
	v_add_u32_e32 v28, s8, v43
	v_ashrrev_i32_e32 v29, 31, v28
	v_and_or_b32 v24, v19, s38, v2
	v_bfe_u32 v2, v35, 16, 1
	v_add3_u32 v2, v35, v2, s37
	v_bfe_u32 v19, v37, 16, 1
	v_lshrrev_b32_e32 v2, 16, v2
	v_add3_u32 v19, v37, v19, s37
	v_and_or_b32 v25, v19, s38, v2
	v_bfe_u32 v2, v49, 16, 1
	v_add3_u32 v2, v49, v2, s37
	v_bfe_u32 v19, v51, 16, 1
	v_lshrrev_b32_e32 v2, 16, v2
	v_add3_u32 v19, v51, v19, s37
	v_and_or_b32 v26, v19, s38, v2
	v_bfe_u32 v2, v53, 16, 1
	v_add3_u32 v2, v53, v2, s37
	v_bfe_u32 v19, v55, 16, 1
	v_lshrrev_b32_e32 v2, 16, v2
	v_add3_u32 v19, v55, v19, s37
	v_lshlrev_b64 v[28:29], 12, v[28:29]
	v_and_or_b32 v27, v19, s38, v2
	ds_read2_b32 v[32:33], v42 offset0:16 offset1:24
	v_lshl_add_u64 v[28:29], v[30:31], 0, v[28:29]
	global_store_dwordx4 v[28:29], v[24:27], off
	ds_read2_b32 v[28:29], v42 offset0:49 offset1:57
	ds_read2_b32 v[34:35], v42 offset0:82 offset1:90
	ds_read2_b32 v[36:37], v42 offset0:115 offset1:123
	s_waitcnt lgkmcnt(3)
	v_bfe_u32 v2, v32, 16, 1
	v_add3_u32 v2, v32, v2, s37
	s_waitcnt lgkmcnt(2)
	v_bfe_u32 v19, v28, 16, 1
	ds_read2_b32 v[48:49], v42 offset0:148 offset1:156
	v_lshrrev_b32_e32 v2, 16, v2
	v_add3_u32 v19, v28, v19, s37
	ds_read2_b32 v[50:51], v42 offset0:181 offset1:189
	v_and_or_b32 v24, v19, s38, v2
	s_waitcnt lgkmcnt(3)
	v_bfe_u32 v2, v34, 16, 1
	v_add3_u32 v2, v34, v2, s37
	s_waitcnt lgkmcnt(2)
	v_bfe_u32 v19, v36, 16, 1
	ds_read2_b32 v[52:53], v42 offset0:214 offset1:222
	v_lshrrev_b32_e32 v2, 16, v2
	v_add3_u32 v19, v36, v19, s37
	ds_read2_b32 v[54:55], v42 offset0:247 offset1:255
	v_and_or_b32 v25, v19, s38, v2
	s_waitcnt lgkmcnt(3)
	v_bfe_u32 v2, v48, 16, 1
	v_add3_u32 v2, v48, v2, s37
	s_waitcnt lgkmcnt(2)
	v_bfe_u32 v19, v50, 16, 1
	v_lshrrev_b32_e32 v2, 16, v2
	v_add3_u32 v19, v50, v19, s37
	v_and_or_b32 v26, v19, s38, v2
	s_waitcnt lgkmcnt(1)
	v_bfe_u32 v2, v52, 16, 1
	v_add3_u32 v2, v52, v2, s37
	s_waitcnt lgkmcnt(0)
	v_bfe_u32 v19, v54, 16, 1
	v_lshrrev_b32_e32 v2, 16, v2
	v_add3_u32 v19, v54, v19, s37
	v_add_u32_e32 v56, s8, v44
	v_and_or_b32 v27, v19, s38, v2
	v_ashrrev_i32_e32 v57, 31, v56
	v_bfe_u32 v19, v33, 16, 1
	v_lshlrev_b64 v[56:57], 12, v[56:57]
	v_bfe_u32 v2, v29, 16, 1
	v_add3_u32 v19, v33, v19, s37
	v_lshl_add_u64 v[56:57], v[30:31], 0, v[56:57]
	v_add3_u32 v2, v29, v2, s37
	v_lshrrev_b32_e32 v19, 16, v19
	global_store_dwordx4 v[56:57], v[24:27], off
	v_add_u32_e32 v28, s8, v45
	v_ashrrev_i32_e32 v29, 31, v28
	v_and_or_b32 v24, v2, s38, v19
	v_bfe_u32 v19, v35, 16, 1
	v_bfe_u32 v2, v37, 16, 1
	v_add3_u32 v19, v35, v19, s37
	v_add3_u32 v2, v37, v2, s37
	v_lshrrev_b32_e32 v19, 16, v19
	v_and_or_b32 v25, v2, s38, v19
	v_bfe_u32 v19, v49, 16, 1
	v_bfe_u32 v2, v51, 16, 1
	v_add3_u32 v19, v49, v19, s37
	v_add3_u32 v2, v51, v2, s37
	v_lshrrev_b32_e32 v19, 16, v19
	v_and_or_b32 v26, v2, s38, v19
	v_bfe_u32 v19, v53, 16, 1
	v_bfe_u32 v2, v55, 16, 1
	v_add3_u32 v19, v53, v19, s37
	v_add3_u32 v2, v55, v2, s37
	v_lshrrev_b32_e32 v19, 16, v19
	v_lshlrev_b64 v[28:29], 12, v[28:29]
	v_and_or_b32 v27, v2, s38, v19
	v_lshl_add_u64 v[28:29], v[30:31], 0, v[28:29]
	global_store_dwordx4 v[28:29], v[24:27], off
	s_waitcnt lgkmcnt(0)
	s_branch .LBB0_15

.LBB0_75:
	v_ashrrev_i32_e32 v0, 31, v18
	v_lshrrev_b32_e32 v0, 17, v0
	v_add_u32_e32 v0, v18, v0
	v_ashrrev_i32_e32 v8, 15, v0
	v_mul_i32_i24_e32 v0, 0x8000, v8
	v_sub_u32_e32 v0, v18, v0
	v_ashrrev_i16_e32 v1, 15, v0
	v_lshrrev_b16_e32 v1, 10, v1
	v_add_u16_e32 v1, v0, v1
	v_ashrrev_i16_e32 v2, 6, v1
	v_and_b32_e32 v1, 0xffffffc0, v1
	v_bfe_i32 v10, v2, 0, 16
	v_sub_u16_e32 v0, v0, v1
	v_ashrrev_i32_e32 v14, 7, v10
	v_ashrrev_i32_sdwa v1, v5, sext(v0) dst_sel:DWORD dst_unused:UNUSED_PAD src0_sel:DWORD src1_sel:WORD_0
	v_cmp_ne_u32_e32 vcc, v14, v1
	v_ashrrev_i32_e32 v9, 31, v8
	s_and_saveexec_b64 s[18:19], vcc
	s_xor_b64 s[18:19], exec, s[18:19]
	s_or_saveexec_b64 s[18:19], s[18:19]
	v_lshlrev_b32_sdwa v12, v16, sext(v0) dst_sel:DWORD dst_unused:UNUSED_PAD src0_sel:DWORD src1_sel:WORD_0
	v_mov_b32_e32 v0, 0
	v_mov_b32_e32 v1, 0
	v_mov_b32_e32 v2, 0
	v_mov_b32_e32 v3, 0
	s_xor_b64 exec, exec, s[18:19]
	s_cbranch_execz .LBB0_74
	v_mov_b32_e32 v0, s2
	ds_read_b128 v[0:3], v0
	v_ashrrev_i32_e32 v15, 31, v14
	v_lshlrev_b64 v[20:21], 9, v[8:9]
	v_and_b32_e32 v6, 0x78, v12
	v_lshlrev_b32_e32 v6, 2, v6
	s_waitcnt lgkmcnt(0)
	v_readfirstlane_b32 s24, v0
	v_readfirstlane_b32 s25, v1
	v_lshlrev_b64 v[0:1], 7, v[14:15]
	v_lshl_add_u64 v[0:1], v[0:1], 0, v[20:21]
	v_and_or_b32 v0, v10, s17, v0
	v_lshlrev_b64 v[0:1], 9, v[0:1]
	v_lshl_add_u64 v[0:1], s[24:25], 0, v[0:1]
	v_lshl_add_u64 v[14:15], v[0:1], 0, v[6:7]
	v_readfirstlane_b32 s24, v2
	v_readfirstlane_b32 s25, v3
	v_lshlrev_b64 v[0:1], 11, v[8:9]
	v_and_b32_e32 v2, 0xffffff80, v10
	v_lshl_add_u64 v[0:1], s[24:25], 0, v[0:1]
	v_ashrrev_i32_e32 v3, 31, v2
	v_lshl_add_u64 v[0:1], v[2:3], 2, v[0:1]
	v_lshl_add_u64 v[32:33], v[0:1], 0, v[6:7]
	global_load_dwordx4 v[0:3], v[32:33], off nt
	global_load_dwordx4 v[20:23], v[14:15], off nt
	global_load_dwordx4 v[24:27], v[14:15], off offset:16 nt
	global_load_dwordx4 v[28:31], v[32:33], off offset:16 nt
	s_waitcnt vmcnt(2)
	v_pk_mul_f32 v[2:3], v[22:23], v[2:3]
	v_pk_mul_f32 v[0:1], v[20:21], v[0:1]
	s_waitcnt vmcnt(0)
	v_pk_mul_f32 v[14:15], v[24:25], v[28:29]
	v_pk_mul_f32 v[20:21], v[26:27], v[30:31]
	v_and_b32_sdwa v11, v0, v17 dst_sel:DWORD dst_unused:UNUSED_PAD src0_sel:WORD_1 src1_sel:DWORD
	v_and_b32_sdwa v13, v3, v17 dst_sel:DWORD dst_unused:UNUSED_PAD src0_sel:WORD_1 src1_sel:DWORD
	v_and_b32_sdwa v19, v1, v17 dst_sel:DWORD dst_unused:UNUSED_PAD src0_sel:WORD_1 src1_sel:DWORD
	v_and_b32_sdwa v23, v14, v17 dst_sel:DWORD dst_unused:UNUSED_PAD src0_sel:WORD_1 src1_sel:DWORD
	v_and_b32_sdwa v25, v20, v17 dst_sel:DWORD dst_unused:UNUSED_PAD src0_sel:WORD_1 src1_sel:DWORD
	v_and_b32_sdwa v6, v2, v17 dst_sel:DWORD dst_unused:UNUSED_PAD src0_sel:WORD_1 src1_sel:DWORD
	v_and_b32_sdwa v22, v15, v17 dst_sel:DWORD dst_unused:UNUSED_PAD src0_sel:WORD_1 src1_sel:DWORD
	v_and_b32_sdwa v24, v21, v17 dst_sel:DWORD dst_unused:UNUSED_PAD src0_sel:WORD_1 src1_sel:DWORD
	v_add3_u32 v0, v0, v11, s20
	v_add3_u32 v3, v3, v13, s20
	v_add3_u32 v1, v1, v19, s20
	v_add3_u32 v11, v14, v23, s20
	v_add3_u32 v14, v20, v25, s20
	v_add3_u32 v2, v2, v6, s20
	v_add3_u32 v6, v15, v22, s20
	v_add3_u32 v13, v21, v24, s20
	v_and_b32_e32 v3, 0xffff0000, v3
	v_and_b32_e32 v15, 0xffff0000, v1
	v_lshrrev_b32_e32 v11, 16, v11
	v_lshrrev_b32_e32 v14, 16, v14
	v_or_b32_sdwa v1, v3, v2 dst_sel:DWORD dst_unused:UNUSED_PAD src0_sel:DWORD src1_sel:WORD_1
	v_or_b32_sdwa v0, v15, v0 dst_sel:DWORD dst_unused:UNUSED_PAD src0_sel:DWORD src1_sel:WORD_1
	v_and_or_b32 v2, v6, s21, v11
	v_and_or_b32 v3, v13, s21, v14
	s_branch .LBB0_74

.LBB0_92:
	s_or_b64 exec, exec, s[8:9]
	global_load_dword v0, v[2:3], off nt
	v_add_u32_e32 v3, 0x200, v5
	v_cmp_lt_i32_e32 vcc, s18, v5
	s_or_b64 s[6:7], vcc, s[6:7]
	s_waitcnt vmcnt(0)
	v_mul_f32_e32 v2, 0xbfb8aa3b, v0
	v_exp_f32_e32 v2, v2
	s_nop 0
	v_add_f32_e32 v2, 1.0, v2
	v_div_scale_f32 v5, s[8:9], v2, v2, v0
	v_rcp_f32_e32 v6, v5
	v_div_scale_f32 v7, vcc, v0, v2, v0
	v_fma_f32 v8, -v5, v6, 1.0
	v_fmac_f32_e32 v6, v8, v6
	v_mul_f32_e32 v8, v7, v6
	v_fma_f32 v9, -v5, v8, v7
	v_fmac_f32_e32 v8, v9, v6
	v_fma_f32 v5, -v5, v8, v7
	v_div_fmas_f32 v5, v5, v6, v8
	v_div_fixup_f32 v0, v5, v2, v0
	ds_write_b32 v4, v0
	v_add_u32_e32 v4, 0x800, v4
	v_mov_b32_e32 v5, v3
	s_andn2_b64 exec, exec, s[6:7]
	s_cbranch_execz .LBB0_97

.LBB0_104:
	v_mul_hi_i32 v3, v2, s38
	s_waitcnt lgkmcnt(0)
	v_readfirstlane_b32 s4, v0
	v_lshrrev_b32_e32 v6, 31, v3
	v_ashrrev_i32_e32 v3, 5, v3
	v_readfirstlane_b32 s5, v1
	s_add_u32 s45, s4, s43
	v_add_u32_e32 v6, v3, v6
	s_addc_u32 s46, s5, s42
	v_mad_u64_u32 v[8:9], s[4:5], v6, s39, v[2:3]
	s_add_u32 s4, s45, s44
	v_ashrrev_i32_e32 v9, 31, v8
	s_addc_u32 s5, s46, 0
	v_lshlrev_b64 v[10:11], 2, v[8:9]
	v_lshl_add_u64 v[12:13], s[4:5], 0, v[10:11]
	global_load_dword v3, v[12:13], off nt
	v_add_u32_e32 v9, 0x200, v2
	v_ashrrev_i32_e32 v7, 31, v6
	v_mov_b64_e32 v[12:13], s[14:15]
	v_cmp_lt_i32_e64 s[4:5], 63, v2
	v_lshl_add_u32 v14, v6, 1, v6
	v_mov_b32_e32 v2, v9
	v_mul_i32_i24_e32 v9, 0x5556, v8
	v_lshl_add_u64 v[6:7], s[8:9], 0, v[6:7]
	v_lshrrev_b32_e32 v15, 31, v9
	v_mad_u64_u32 v[12:13], s[46:47], v6, s19, v[12:13]
	v_add_u16_sdwa v9, v9, v15 dst_sel:DWORD dst_unused:UNUSED_PAD src0_sel:WORD_1 src1_sel:DWORD
	v_mov_b32_e32 v6, v13
	s_or_b64 s[16:17], s[4:5], s[16:17]
	v_mul_lo_u16_e32 v13, 3, v9
	v_mad_u64_u32 v[6:7], s[4:5], v7, s19, v[6:7]
	v_sub_u16_e32 v7, v8, v13
	v_mov_b32_e32 v13, v6
	v_bfe_i32 v6, v7, 0, 16
	v_lshlrev_b32_sdwa v9, v21, sext(v9) dst_sel:DWORD dst_unused:UNUSED_PAD src0_sel:DWORD src1_sel:WORD_0
	v_add_lshl_u32 v6, v14, v6, 8
	v_add3_u32 v14, 0, v9, v6
	ds_read2st64_b32 v[6:7], v14 offset0:96 offset1:105
	v_lshl_add_u64 v[8:9], v[12:13], 0, v[10:11]
	ds_read2st64_b32 v[10:11], v14 offset0:114 offset1:123
	ds_read2st64_b32 v[12:13], v14 offset0:132 offset1:141
	ds_read2st64_b32 v[14:15], v14 offset0:150 offset1:159
	s_waitcnt vmcnt(0) lgkmcnt(3)
	v_add_f32_e32 v3, v3, v6
	v_add_f32_e32 v3, v3, v7
	s_waitcnt lgkmcnt(2)
	v_add_f32_e32 v3, v3, v10
	v_add_f32_e32 v3, v3, v11
	s_waitcnt lgkmcnt(1)
	v_add_f32_e32 v3, v3, v12
	v_add_f32_e32 v3, v3, v13
	s_waitcnt lgkmcnt(0)
	v_add_f32_e32 v3, v3, v14
	v_add_f32_e32 v3, v3, v15
	global_store_dword v[8:9], v3, off
	s_andn2_b64 exec, exec, s[16:17]
	s_cbranch_execnz .LBB0_104
	s_branch .LBB0_99
